# GEMM K-loops: priority inverted (load segments at s_setprio 1, MFMA segments at 0), aligned loop heads
# baseline (speedup 1.0000x reference)
; #define PG8_STAGE(bufoff, gbase, voff) do { _Pragma("unroll") for (int _i = 0; _i < 2; ++_i) \
;         __builtin_amdgcn_global_load_lds((const unsigned*)((const char*)(gbase) + (voff)[_i]), (LAS unsigned*)(lds + (bufoff) + ldsw + _i * 8192), 16, 0, 0); } while (0)
; #define PG8_LDA(dst, b, h) do { _Pragma("unroll") for (int m = 0; m < 4; ++m) _Pragma("unroll") for (int k = 0; k < 2; ++k) dst[m][k] = *(const LAS bf16x8*)(lds + PG8_SA(b, h) + aoff + m * 2048 + k * 1024); } while (0)
; #define PG8_LDB(dst, b, h) do { _Pragma("unroll") for (int n = 0; n < 2; ++n) _Pragma("unroll") for (int k = 0; k < 2; ++k) dst[n][k] = *(const LAS bf16x8*)(lds + PG8_SB(b, h) + boff + n * 2048 + k * 1024); } while (0)
; #define PG8_SCHED __builtin_amdgcn_sched_barrier(0)
; template <class Epi, class Sched>
; __device__ __forceinline__ void gemm_phase(LAS unsigned char* lds, const Gemm g, const Sched& S, const Epi& E) {
;     ...
;         const bool has_next = S.next(ui + 1, nxt);
;         const size_t nko = (has_next && nxt.kc > 0) ? (size_t)nxt.kc * nts * kstep : 0;
;         const char* nA = has_next ? (const char*)g.A + (size_t)nxt.pm * tstep + nko : cA; const char* nB = has_next ? (const char*)g.Bt + (size_t)nxt.pn * tstep + nko : cB;
;         const int nt = cur.kc >= 0 ? nts : ntf;
;         for (int t = 0; t < nt; t += 2) {
;             const bool last = (t == nt - 2);
;             const char* a1 = cA + (size_t)(t + 1) * kstep;
;             const char* a2 = last ? nA : cA + (size_t)(t + 2) * kstep; const char* b2 = last ? nB : cB + (size_t)(t + 2) * kstep;
;             const char* a3 = a2 + kstep; const char* b3 = b2 + kstep;
;             PG8_LDB(B0, 0, 0); PG8_LDB(B1, 0, 1); PG8_SCHED; PG8_LDA(At, 0, 0); PG8_STAGE(PG8_SA(1, 1), a1 + hstep, voffA);
;     ...
; #pragma unroll
;         for (int a = 0; a < 2; ++a)
; #pragma unroll
;             for (int b = 0; b < 2; ++b)
; #pragma unroll
;                 for (int m = 0; m < 4; ++m)
; #pragma unroll
;                     for (int n = 0; n < 2; ++n) acc[a][b][m][n] = (f32x4){0.f, 0.f, 0.f, 0.f};
.LBB0_502:
	s_ashr_i32 s51, s50, 31
	s_lshl_b64 s[12:13], s[50:51], 19
	s_add_u32 s54, s92, s12
	s_addc_u32 s55, s93, s13
	s_and_b64 s[12:13], s[38:39], exec
	s_cselect_b32 s7, s55, s15
	s_cselect_b32 s8, s54, s14
	s_ashr_i32 s53, s52, 31
	s_lshl_b64 s[12:13], s[52:53], 19
	s_add_u32 s56, s24, s12
	s_addc_u32 s57, s25, s13
	s_and_b64 s[12:13], s[38:39], exec
	s_cselect_b32 s12, s57, s17
	s_cselect_b32 s13, s56, s16
	s_add_u32 s14, s14, 0x40080
	s_addc_u32 s15, s15, 0
	s_add_u32 s21, s16, 0x100
	v_mov_b32_e32 v0, 0
	s_addc_u32 s33, s17, 0
	s_mov_b32 s40, -2
	v_mov_b32_e32 v1, v0
	s_waitcnt lgkmcnt(0)
	v_mov_b32_e32 v2, v0
	v_mov_b32_e32 v3, v0
	v_mov_b32_e32 v4, v0
	v_mov_b32_e32 v5, v0
	v_mov_b32_e32 v6, v0
	v_mov_b32_e32 v7, v0
	v_mov_b32_e32 v16, v0
	v_mov_b32_e32 v17, v0
	v_mov_b32_e32 v18, v0
	v_mov_b32_e32 v19, v0
	v_mov_b32_e32 v20, v0
	v_mov_b32_e32 v21, v0
	v_mov_b32_e32 v22, v0
	v_mov_b32_e32 v23, v0
	v_mov_b32_e32 v32, v0
	v_mov_b32_e32 v33, v0
	v_mov_b32_e32 v34, v0
	v_mov_b32_e32 v35, v0
	v_mov_b32_e32 v36, v0
	v_mov_b32_e32 v37, v0
	v_mov_b32_e32 v38, v0
	v_mov_b32_e32 v39, v0
	v_mov_b32_e32 v48, v0
	v_mov_b32_e32 v49, v0
	v_mov_b32_e32 v50, v0
	v_mov_b32_e32 v51, v0
	v_mov_b32_e32 v52, v0
	v_mov_b32_e32 v53, v0
	v_mov_b32_e32 v54, v0
	v_mov_b32_e32 v55, v0
	v_mov_b32_e32 v8, v0
	v_mov_b32_e32 v9, v0
	v_mov_b32_e32 v10, v0
	v_mov_b32_e32 v11, v0
	v_mov_b32_e32 v12, v0
	v_mov_b32_e32 v13, v0
	v_mov_b32_e32 v14, v0
	v_mov_b32_e32 v15, v0
	v_mov_b32_e32 v24, v0
	v_mov_b32_e32 v25, v0
	v_mov_b32_e32 v26, v0
	v_mov_b32_e32 v27, v0
	v_mov_b32_e32 v28, v0
	v_mov_b32_e32 v29, v0
	v_mov_b32_e32 v30, v0
	v_mov_b32_e32 v31, v0
	v_mov_b32_e32 v40, v0
	v_mov_b32_e32 v41, v0
	v_mov_b32_e32 v42, v0
	v_mov_b32_e32 v43, v0
	v_mov_b32_e32 v44, v0
	v_mov_b32_e32 v45, v0
	v_mov_b32_e32 v46, v0
	v_mov_b32_e32 v47, v0
	v_mov_b32_e32 v56, v0
	v_mov_b32_e32 v57, v0
	v_mov_b32_e32 v58, v0
	v_mov_b32_e32 v59, v0
	v_mov_b32_e32 v60, v0
	v_mov_b32_e32 v61, v0
	v_mov_b32_e32 v62, v0
	v_mov_b32_e32 v63, v0
	v_mov_b32_e32 v64, v0
	v_mov_b32_e32 v65, v0
	v_mov_b32_e32 v66, v0
	v_mov_b32_e32 v67, v0
	v_mov_b32_e32 v68, v0
	v_mov_b32_e32 v69, v0
	v_mov_b32_e32 v70, v0
	v_mov_b32_e32 v71, v0
	v_mov_b32_e32 v96, v0
	v_mov_b32_e32 v97, v0
	v_mov_b32_e32 v98, v0
	v_mov_b32_e32 v99, v0
	v_mov_b32_e32 v100, v0
	v_mov_b32_e32 v101, v0
	v_mov_b32_e32 v102, v0
	v_mov_b32_e32 v103, v0
	v_mov_b32_e32 v112, v0
	v_mov_b32_e32 v113, v0
	v_mov_b32_e32 v114, v0
	v_mov_b32_e32 v115, v0
	v_mov_b32_e32 v116, v0
	v_mov_b32_e32 v117, v0
	v_mov_b32_e32 v118, v0
	v_mov_b32_e32 v119, v0
	v_mov_b32_e32 v128, v0
	v_mov_b32_e32 v129, v0
	v_mov_b32_e32 v130, v0
	v_mov_b32_e32 v131, v0
	v_mov_b32_e32 v132, v0
	v_mov_b32_e32 v133, v0
	v_mov_b32_e32 v134, v0
	v_mov_b32_e32 v135, v0
	v_mov_b32_e32 v88, v0
	v_mov_b32_e32 v89, v0
	v_mov_b32_e32 v90, v0
	v_mov_b32_e32 v91, v0
	v_mov_b32_e32 v92, v0
	v_mov_b32_e32 v93, v0
	v_mov_b32_e32 v94, v0
	v_mov_b32_e32 v95, v0
	v_mov_b32_e32 v104, v0
	v_mov_b32_e32 v105, v0
	v_mov_b32_e32 v106, v0
	v_mov_b32_e32 v107, v0
	v_mov_b32_e32 v108, v0
	v_mov_b32_e32 v109, v0
	v_mov_b32_e32 v110, v0
	v_mov_b32_e32 v111, v0
	v_mov_b32_e32 v120, v0
	v_mov_b32_e32 v121, v0
	v_mov_b32_e32 v122, v0
	v_mov_b32_e32 v123, v0
	v_mov_b32_e32 v124, v0
	v_mov_b32_e32 v125, v0
	v_mov_b32_e32 v126, v0
	v_mov_b32_e32 v127, v0
	v_mov_b32_e32 v136, v0
	v_mov_b32_e32 v137, v0
	v_mov_b32_e32 v138, v0
	v_mov_b32_e32 v139, v0
	v_mov_b32_e32 v140, v0
	v_mov_b32_e32 v141, v0
	v_mov_b32_e32 v142, v0
	v_mov_b32_e32 v143, v0
	s_setprio 1
	.p2align	6
.LBB0_503:
	s_add_u32 s16, s14, 0xfffc0080
	s_addc_u32 s17, s15, -1
	s_add_i32 s41, 0, 0x10000
	s_cmp_eq_u32 s40, 12
	s_cselect_b32 s19, s7, s17
	s_cselect_b32 s18, s8, s16
	s_cselect_b32 s17, s12, s33
	s_cselect_b32 s16, s13, s21
	s_add_i32 s51, 0, 0x14000
	v_add_u32_e32 v84, s41, v168
	v_add_u32_e32 v170, s51, v168
	ds_read_b128 v[72:75], v84
	ds_read_b128 v[76:79], v84 offset:1024
	ds_read_b128 v[80:83], v84 offset:2048
	ds_read_b128 v[84:87], v84 offset:3072
	ds_read_b128 v[154:157], v170
	ds_read_b128 v[158:161], v170 offset:1024
	ds_read_b128 v[162:165], v170 offset:2048
	ds_read_b128 v[170:173], v170 offset:3072
	v_lshl_add_u64 v[178:179], s[14:15], 0, v[150:151]
	s_add_i32 m0, s26, 0xc000
	ds_read_b128 v[174:177], v169
	ds_read_b128 v[192:195], v169 offset:1024
	ds_read_b128 v[196:199], v169 offset:2048
	ds_read_b128 v[200:203], v169 offset:3072
	ds_read_b128 v[204:207], v169 offset:4096
	ds_read_b128 v[208:211], v169 offset:5120
	ds_read_b128 v[212:215], v169 offset:6144
	ds_read_b128 v[230:233], v169 offset:7168
	global_load_lds_dwordx4 v[178:179], off
	v_lshl_add_u64 v[178:179], s[14:15], 0, v[152:153]
	s_add_i32 m0, s26, 0xe000
	s_nop 0
	global_load_lds_dwordx4 v[178:179], off
	s_waitcnt vmcnt(8)
	s_waitcnt lgkmcnt(0)
	s_barrier
; #define PG8_STAGE(bufoff, gbase, voff) do { _Pragma("unroll") for (int _i = 0; _i < 2; ++_i) \
;         __builtin_amdgcn_global_load_lds((const unsigned*)((const char*)(gbase) + (voff)[_i]), (LAS unsigned*)(lds + (bufoff) + ldsw + _i * 8192), 16, 0, 0); } while (0)
; #define PG8_LDA(dst, b, h) do { _Pragma("unroll") for (int m = 0; m < 4; ++m) _Pragma("unroll") for (int k = 0; k < 2; ++k) dst[m][k] = *(const LAS bf16x8*)(lds + PG8_SA(b, h) + aoff + m * 2048 + k * 1024); } while (0)
; #define PG8_MMA(ai, bj, At, Bt) do { __builtin_amdgcn_s_setprio(1); _Pragma("unroll") for (int m = 0; m < 4; ++m) _Pragma("unroll") for (int n = 0; n < 2; ++n) _Pragma("unroll") for (int k = 0; k < 2; ++k) \
;         acc[ai][bj][m][n] = __builtin_amdgcn_mfma_f32_16x16x32_bf16(Bt[n][k], At[m][k], acc[ai][bj][m][n], 0, 0, 0); __builtin_amdgcn_s_setprio(0); } while (0)
; #define PG8_WAIT_V(n) asm volatile("s_waitcnt vmcnt(" #n ")" ::: "memory")
; #define PG8_WAIT_L(n) asm volatile("s_waitcnt lgkmcnt(" #n ")" ::: "memory")
; #define PG8_BAR __builtin_amdgcn_s_barrier()
; #define PG8_SCHED __builtin_amdgcn_sched_barrier(0)
; template <class Epi, class Sched>
; __device__ __forceinline__ void gemm_phase(LAS unsigned char* lds, const Gemm g, const Sched& S, const Epi& E) {
;     ...
;             PG8_WAIT_V(8); PG8_WAIT_L(0); PG8_BAR; PG8_MMA(0, 0, At, B0); PG8_MMA(0, 1, At, B1); PG8_BAR; PG8_SCHED;
;             PG8_LDA(At, 0, 1); PG8_STAGE(PG8_SB(0, 0), b2, voffB); PG8_STAGE(PG8_SB(0, 1), b2 + hstep, voffB); PG8_STAGE(PG8_SA(0, 0), a2, voffA);
;             PG8_WAIT_V(8); PG8_WAIT_L(0); PG8_BAR; PG8_MMA(1, 0, At, B0); PG8_MMA(1, 1, At, B1); PG8_BAR; PG8_SCHED;
	s_setprio 0
	s_waitcnt lgkmcnt(0)
	v_mfma_f32_16x16x32_bf16 v[140:143], v[72:75], v[174:177], v[140:143]
	v_mfma_f32_16x16x32_bf16 v[136:139], v[80:83], v[174:177], v[136:139]
	v_mfma_f32_16x16x32_bf16 v[124:127], v[72:75], v[196:199], v[124:127]
	v_mfma_f32_16x16x32_bf16 v[120:123], v[80:83], v[196:199], v[120:123]
	v_mfma_f32_16x16x32_bf16 v[108:111], v[72:75], v[204:207], v[108:111]
	v_mfma_f32_16x16x32_bf16 v[104:107], v[80:83], v[204:207], v[104:107]
	v_mfma_f32_16x16x32_bf16 v[92:95], v[72:75], v[212:215], v[92:95]
	v_mfma_f32_16x16x32_bf16 v[88:91], v[80:83], v[212:215], v[88:91]
	v_mfma_f32_16x16x32_bf16 v[140:143], v[76:79], v[192:195], v[140:143]
	v_mfma_f32_16x16x32_bf16 v[136:139], v[84:87], v[192:195], v[136:139]
	v_mfma_f32_16x16x32_bf16 v[124:127], v[76:79], v[200:203], v[124:127]
	v_mfma_f32_16x16x32_bf16 v[120:123], v[84:87], v[200:203], v[120:123]
	v_mfma_f32_16x16x32_bf16 v[108:111], v[76:79], v[208:211], v[108:111]
	v_mfma_f32_16x16x32_bf16 v[104:107], v[84:87], v[208:211], v[104:107]
	v_mfma_f32_16x16x32_bf16 v[92:95], v[76:79], v[230:233], v[92:95]
	v_mfma_f32_16x16x32_bf16 v[88:91], v[84:87], v[230:233], v[88:91]
	v_mfma_f32_16x16x32_bf16 v[132:135], v[154:157], v[174:177], v[132:135]
	v_mfma_f32_16x16x32_bf16 v[128:131], v[162:165], v[174:177], v[128:131]
	v_mfma_f32_16x16x32_bf16 v[116:119], v[154:157], v[196:199], v[116:119]
	v_mfma_f32_16x16x32_bf16 v[112:115], v[162:165], v[196:199], v[112:115]
	v_mfma_f32_16x16x32_bf16 v[100:103], v[154:157], v[204:207], v[100:103]
	v_mfma_f32_16x16x32_bf16 v[96:99], v[162:165], v[204:207], v[96:99]
	v_mfma_f32_16x16x32_bf16 v[68:71], v[154:157], v[212:215], v[68:71]
	v_mfma_f32_16x16x32_bf16 v[64:67], v[162:165], v[212:215], v[64:67]
	v_mfma_f32_16x16x32_bf16 v[132:135], v[158:161], v[192:195], v[132:135]
	v_mfma_f32_16x16x32_bf16 v[128:131], v[170:173], v[192:195], v[128:131]
	v_mfma_f32_16x16x32_bf16 v[116:119], v[158:161], v[200:203], v[116:119]
	v_mfma_f32_16x16x32_bf16 v[112:115], v[170:173], v[200:203], v[112:115]
	v_mfma_f32_16x16x32_bf16 v[100:103], v[158:161], v[208:211], v[100:103]
	v_mfma_f32_16x16x32_bf16 v[96:99], v[170:173], v[208:211], v[96:99]
	v_mfma_f32_16x16x32_bf16 v[68:71], v[158:161], v[230:233], v[68:71]
	v_mfma_f32_16x16x32_bf16 v[64:67], v[170:173], v[230:233], v[64:67]
	s_barrier
	s_setprio 1
	s_add_i32 s41, s41, s23
	v_lshl_add_u64 v[178:179], s[16:17], 0, v[184:185]
	s_mov_b32 m0, s41
	ds_read_b128 v[174:177], v169 offset:16384
	ds_read_b128 v[192:195], v169 offset:17408
	ds_read_b128 v[196:199], v169 offset:18432
	ds_read_b128 v[200:203], v169 offset:19456
	ds_read_b128 v[204:207], v169 offset:20480
	ds_read_b128 v[208:211], v169 offset:21504
	ds_read_b128 v[212:215], v169 offset:22528
	ds_read_b128 v[230:233], v169 offset:23552
	global_load_lds_dwordx4 v[178:179], off
	s_add_i32 m0, s41, 0x2000
	s_add_u32 s42, s16, 0x40000
	v_lshl_add_u64 v[216:217], s[16:17], 0, v[148:149]
	s_addc_u32 s43, s17, 0
	s_add_i32 s41, s51, s23
	global_load_lds_dwordx4 v[216:217], off
	v_lshl_add_u64 v[234:235], s[42:43], 0, v[184:185]
	s_mov_b32 m0, s41
	v_lshl_add_u64 v[236:237], s[18:19], 0, v[146:147]
	global_load_lds_dwordx4 v[234:235], off
	v_lshl_add_u64 v[234:235], s[42:43], 0, v[148:149]
	s_add_i32 m0, s41, 0x2000
	s_nop 0
	global_load_lds_dwordx4 v[234:235], off
	v_lshl_add_u64 v[234:235], s[18:19], 0, v[144:145]
	s_mov_b32 m0, s26
	s_nop 0
	global_load_lds_dwordx4 v[234:235], off
	s_mov_b32 m0, s27
	s_nop 0
	global_load_lds_dwordx4 v[236:237], off
	s_waitcnt vmcnt(8)
	s_waitcnt lgkmcnt(0)
	s_barrier
	s_setprio 0
	s_waitcnt lgkmcnt(0)
	v_mfma_f32_16x16x32_bf16 v[60:63], v[72:75], v[174:177], v[60:63]
	v_mfma_f32_16x16x32_bf16 v[56:59], v[80:83], v[174:177], v[56:59]
	v_mfma_f32_16x16x32_bf16 v[44:47], v[72:75], v[196:199], v[44:47]
	v_mfma_f32_16x16x32_bf16 v[40:43], v[80:83], v[196:199], v[40:43]
	v_mfma_f32_16x16x32_bf16 v[28:31], v[72:75], v[204:207], v[28:31]
	v_mfma_f32_16x16x32_bf16 v[24:27], v[80:83], v[204:207], v[24:27]
	v_mfma_f32_16x16x32_bf16 v[12:15], v[72:75], v[212:215], v[12:15]
	v_mfma_f32_16x16x32_bf16 v[8:11], v[80:83], v[212:215], v[8:11]
	v_mfma_f32_16x16x32_bf16 v[60:63], v[76:79], v[192:195], v[60:63]
	v_mfma_f32_16x16x32_bf16 v[56:59], v[84:87], v[192:195], v[56:59]
	v_mfma_f32_16x16x32_bf16 v[44:47], v[76:79], v[200:203], v[44:47]
	v_mfma_f32_16x16x32_bf16 v[40:43], v[84:87], v[200:203], v[40:43]
	v_mfma_f32_16x16x32_bf16 v[28:31], v[76:79], v[208:211], v[28:31]
	v_mfma_f32_16x16x32_bf16 v[24:27], v[84:87], v[208:211], v[24:27]
	v_mfma_f32_16x16x32_bf16 v[12:15], v[76:79], v[230:233], v[12:15]
	v_mfma_f32_16x16x32_bf16 v[8:11], v[84:87], v[230:233], v[8:11]
	v_mfma_f32_16x16x32_bf16 v[52:55], v[154:157], v[174:177], v[52:55]
	v_mfma_f32_16x16x32_bf16 v[48:51], v[162:165], v[174:177], v[48:51]
	v_mfma_f32_16x16x32_bf16 v[36:39], v[154:157], v[196:199], v[36:39]
	v_mfma_f32_16x16x32_bf16 v[32:35], v[162:165], v[196:199], v[32:35]
	v_mfma_f32_16x16x32_bf16 v[20:23], v[154:157], v[204:207], v[20:23]
	v_mfma_f32_16x16x32_bf16 v[16:19], v[162:165], v[204:207], v[16:19]
	v_mfma_f32_16x16x32_bf16 v[4:7], v[154:157], v[212:215], v[4:7]
	v_mfma_f32_16x16x32_bf16 v[0:3], v[162:165], v[212:215], v[0:3]
	v_mfma_f32_16x16x32_bf16 v[52:55], v[158:161], v[192:195], v[52:55]
	v_mfma_f32_16x16x32_bf16 v[48:51], v[170:173], v[192:195], v[48:51]
	v_mfma_f32_16x16x32_bf16 v[36:39], v[158:161], v[200:203], v[36:39]
	v_mfma_f32_16x16x32_bf16 v[32:35], v[170:173], v[200:203], v[32:35]
	v_mfma_f32_16x16x32_bf16 v[20:23], v[158:161], v[208:211], v[20:23]
	v_mfma_f32_16x16x32_bf16 v[16:19], v[170:173], v[208:211], v[16:19]
	v_mfma_f32_16x16x32_bf16 v[4:7], v[158:161], v[230:233], v[4:7]
	v_mfma_f32_16x16x32_bf16 v[0:3], v[170:173], v[230:233], v[0:3]
	s_barrier
; #define PG8_STAGE(bufoff, gbase, voff) do { _Pragma("unroll") for (int _i = 0; _i < 2; ++_i) \
;         __builtin_amdgcn_global_load_lds((const unsigned*)((const char*)(gbase) + (voff)[_i]), (LAS unsigned*)(lds + (bufoff) + ldsw + _i * 8192), 16, 0, 0); } while (0)
; #define PG8_LDA(dst, b, h) do { _Pragma("unroll") for (int m = 0; m < 4; ++m) _Pragma("unroll") for (int k = 0; k < 2; ++k) dst[m][k] = *(const LAS bf16x8*)(lds + PG8_SA(b, h) + aoff + m * 2048 + k * 1024); } while (0)
; #define PG8_LDB(dst, b, h) do { _Pragma("unroll") for (int n = 0; n < 2; ++n) _Pragma("unroll") for (int k = 0; k < 2; ++k) dst[n][k] = *(const LAS bf16x8*)(lds + PG8_SB(b, h) + boff + n * 2048 + k * 1024); } while (0)
; #define PG8_MMA(ai, bj, At, Bt) do { __builtin_amdgcn_s_setprio(1); _Pragma("unroll") for (int m = 0; m < 4; ++m) _Pragma("unroll") for (int n = 0; n < 2; ++n) _Pragma("unroll") for (int k = 0; k < 2; ++k) \
;         acc[ai][bj][m][n] = __builtin_amdgcn_mfma_f32_16x16x32_bf16(Bt[n][k], At[m][k], acc[ai][bj][m][n], 0, 0, 0); __builtin_amdgcn_s_setprio(0); } while (0)
; #define PG8_WAIT_V(n) asm volatile("s_waitcnt vmcnt(" #n ")" ::: "memory")
; #define PG8_WAIT_L(n) asm volatile("s_waitcnt lgkmcnt(" #n ")" ::: "memory")
; #define PG8_BAR __builtin_amdgcn_s_barrier()
; #define PG8_SCHED __builtin_amdgcn_sched_barrier(0)
; template <class Epi, class Sched>
; __device__ __forceinline__ void gemm_phase(LAS unsigned char* lds, const Gemm g, const Sched& S, const Epi& E) {
;     ...
;             PG8_LDB(B0, 1, 0); PG8_LDB(B1, 1, 1); PG8_SCHED; PG8_LDA(At, 1, 0); PG8_STAGE(PG8_SA(0, 1), a2 + hstep, voffA);
;             PG8_WAIT_V(8); PG8_WAIT_L(0); PG8_BAR; PG8_MMA(0, 0, At, B0); PG8_MMA(0, 1, At, B1); PG8_BAR; PG8_SCHED;
	s_setprio 1
	s_add_i32 s41, 0, 0x18000
	s_add_i32 s42, 0, 0x1c000
	v_add_u32_e32 v84, s41, v168
	v_add_u32_e32 v170, s42, v168
	ds_read_b128 v[72:75], v84
	ds_read_b128 v[76:79], v84 offset:1024
	ds_read_b128 v[80:83], v84 offset:2048
	ds_read_b128 v[84:87], v84 offset:3072
	ds_read_b128 v[154:157], v170
	ds_read_b128 v[158:161], v170 offset:1024
	ds_read_b128 v[162:165], v170 offset:2048
	ds_read_b128 v[170:173], v170 offset:3072
	s_add_u32 s18, s18, 0x40000
	s_addc_u32 s19, s19, 0
	s_mov_b32 m0, s28
	v_lshl_add_u64 v[238:239], s[18:19], 0, v[144:145]
	ds_read_b128 v[174:177], v169 offset:32768
	ds_read_b128 v[192:195], v169 offset:33792
	ds_read_b128 v[196:199], v169 offset:34816
	ds_read_b128 v[200:203], v169 offset:35840
	ds_read_b128 v[204:207], v169 offset:36864
	ds_read_b128 v[208:211], v169 offset:37888
	ds_read_b128 v[212:215], v169 offset:38912
	ds_read_b128 v[230:233], v169 offset:39936
	global_load_lds_dwordx4 v[238:239], off
	v_lshl_add_u64 v[238:239], s[18:19], 0, v[146:147]
	s_mov_b32 m0, s29
	s_nop 0
	global_load_lds_dwordx4 v[238:239], off
	s_waitcnt vmcnt(8)
	s_waitcnt lgkmcnt(0)
	s_barrier
	s_setprio 0
	s_waitcnt lgkmcnt(0)
	v_mfma_f32_16x16x32_bf16 v[140:143], v[72:75], v[174:177], v[140:143]
	v_mfma_f32_16x16x32_bf16 v[136:139], v[80:83], v[174:177], v[136:139]
	v_mfma_f32_16x16x32_bf16 v[124:127], v[72:75], v[196:199], v[124:127]
	v_mfma_f32_16x16x32_bf16 v[120:123], v[80:83], v[196:199], v[120:123]
	v_mfma_f32_16x16x32_bf16 v[108:111], v[72:75], v[204:207], v[108:111]
	v_mfma_f32_16x16x32_bf16 v[104:107], v[80:83], v[204:207], v[104:107]
	v_mfma_f32_16x16x32_bf16 v[92:95], v[72:75], v[212:215], v[92:95]
	v_mfma_f32_16x16x32_bf16 v[88:91], v[80:83], v[212:215], v[88:91]
	v_mfma_f32_16x16x32_bf16 v[140:143], v[76:79], v[192:195], v[140:143]
	v_mfma_f32_16x16x32_bf16 v[136:139], v[84:87], v[192:195], v[136:139]
	v_mfma_f32_16x16x32_bf16 v[124:127], v[76:79], v[200:203], v[124:127]
	v_mfma_f32_16x16x32_bf16 v[120:123], v[84:87], v[200:203], v[120:123]
	v_mfma_f32_16x16x32_bf16 v[108:111], v[76:79], v[208:211], v[108:111]
	v_mfma_f32_16x16x32_bf16 v[104:107], v[84:87], v[208:211], v[104:107]
	v_mfma_f32_16x16x32_bf16 v[92:95], v[76:79], v[230:233], v[92:95]
	v_mfma_f32_16x16x32_bf16 v[88:91], v[84:87], v[230:233], v[88:91]
	v_mfma_f32_16x16x32_bf16 v[132:135], v[154:157], v[174:177], v[132:135]
	v_mfma_f32_16x16x32_bf16 v[128:131], v[162:165], v[174:177], v[128:131]
	v_mfma_f32_16x16x32_bf16 v[116:119], v[154:157], v[196:199], v[116:119]
	v_mfma_f32_16x16x32_bf16 v[112:115], v[162:165], v[196:199], v[112:115]
	v_mfma_f32_16x16x32_bf16 v[100:103], v[154:157], v[204:207], v[100:103]
	v_mfma_f32_16x16x32_bf16 v[96:99], v[162:165], v[204:207], v[96:99]
	v_mfma_f32_16x16x32_bf16 v[68:71], v[154:157], v[212:215], v[68:71]
	v_mfma_f32_16x16x32_bf16 v[64:67], v[162:165], v[212:215], v[64:67]
	v_mfma_f32_16x16x32_bf16 v[132:135], v[158:161], v[192:195], v[132:135]
	v_mfma_f32_16x16x32_bf16 v[128:131], v[170:173], v[192:195], v[128:131]
	v_mfma_f32_16x16x32_bf16 v[116:119], v[158:161], v[200:203], v[116:119]
	v_mfma_f32_16x16x32_bf16 v[112:115], v[170:173], v[200:203], v[112:115]
	v_mfma_f32_16x16x32_bf16 v[100:103], v[158:161], v[208:211], v[100:103]
	v_mfma_f32_16x16x32_bf16 v[96:99], v[170:173], v[208:211], v[96:99]
	v_mfma_f32_16x16x32_bf16 v[68:71], v[158:161], v[230:233], v[68:71]
	v_mfma_f32_16x16x32_bf16 v[64:67], v[170:173], v[230:233], v[64:67]
	s_barrier
; #define PG8_STAGE(bufoff, gbase, voff) do { _Pragma("unroll") for (int _i = 0; _i < 2; ++_i) \
;         __builtin_amdgcn_global_load_lds((const unsigned*)((const char*)(gbase) + (voff)[_i]), (LAS unsigned*)(lds + (bufoff) + ldsw + _i * 8192), 16, 0, 0); } while (0)
; #define PG8_LDA(dst, b, h) do { _Pragma("unroll") for (int m = 0; m < 4; ++m) _Pragma("unroll") for (int k = 0; k < 2; ++k) dst[m][k] = *(const LAS bf16x8*)(lds + PG8_SA(b, h) + aoff + m * 2048 + k * 1024); } while (0)
; #define PG8_MMA(ai, bj, At, Bt) do { __builtin_amdgcn_s_setprio(1); _Pragma("unroll") for (int m = 0; m < 4; ++m) _Pragma("unroll") for (int n = 0; n < 2; ++n) _Pragma("unroll") for (int k = 0; k < 2; ++k) \
;         acc[ai][bj][m][n] = __builtin_amdgcn_mfma_f32_16x16x32_bf16(Bt[n][k], At[m][k], acc[ai][bj][m][n], 0, 0, 0); __builtin_amdgcn_s_setprio(0); } while (0)
; #define PG8_WAIT_V(n) asm volatile("s_waitcnt vmcnt(" #n ")" ::: "memory")
; #define PG8_WAIT_L(n) asm volatile("s_waitcnt lgkmcnt(" #n ")" ::: "memory")
; #define PG8_BAR __builtin_amdgcn_s_barrier()
; #define PG8_SCHED __builtin_amdgcn_sched_barrier(0)
; template <class Epi, class Sched>
; __device__ __forceinline__ void gemm_phase(LAS unsigned char* lds, const Gemm g, const Sched& S, const Epi& E) {
;     ...
;             PG8_LDA(At, 1, 1); PG8_STAGE(PG8_SB(1, 0), b3, voffB); PG8_STAGE(PG8_SB(1, 1), b3 + hstep, voffB); PG8_STAGE(PG8_SA(1, 0), a3, voffA);
;             PG8_WAIT_V(8); PG8_WAIT_L(0); PG8_BAR; PG8_MMA(1, 0, At, B0); PG8_MMA(1, 1, At, B1); PG8_BAR; PG8_SCHED;
;         }
;         if (wr == 0) PG8_BAR;
	s_setprio 1
	s_add_i32 s18, s41, s23
	v_lshl_add_u64 v[178:179], v[178:179], 0, s[84:85]
	s_mov_b32 m0, s18
	ds_read_b128 v[174:177], v169 offset:49152
	ds_read_b128 v[192:195], v169 offset:50176
	ds_read_b128 v[196:199], v169 offset:51200
	ds_read_b128 v[200:203], v169 offset:52224
	ds_read_b128 v[204:207], v169 offset:53248
	ds_read_b128 v[208:211], v169 offset:54272
	ds_read_b128 v[212:215], v169 offset:55296
	ds_read_b128 v[230:233], v169 offset:56320
	global_load_lds_dwordx4 v[178:179], off
	s_add_i32 m0, s18, 0x2000
	s_add_u32 s16, s16, 0x40080
	v_lshl_add_u64 v[178:179], v[216:217], 0, s[84:85]
	s_addc_u32 s17, s17, 0
	s_add_i32 s18, s42, s23
	global_load_lds_dwordx4 v[178:179], off
	v_lshl_add_u64 v[178:179], s[16:17], 0, v[184:185]
	s_mov_b32 m0, s18
	s_nop 0
	global_load_lds_dwordx4 v[178:179], off
	v_lshl_add_u64 v[178:179], s[16:17], 0, v[148:149]
	s_add_i32 m0, s18, 0x2000
	s_nop 0
	global_load_lds_dwordx4 v[178:179], off
	v_lshl_add_u64 v[178:179], v[234:235], 0, s[84:85]
	s_mov_b32 m0, s34
	s_nop 0
	global_load_lds_dwordx4 v[178:179], off
	v_lshl_add_u64 v[178:179], v[236:237], 0, s[84:85]
	s_mov_b32 m0, s35
	s_nop 0
	global_load_lds_dwordx4 v[178:179], off
	s_waitcnt vmcnt(8)
	s_waitcnt lgkmcnt(0)
	s_barrier
	s_setprio 0
	s_waitcnt lgkmcnt(0)
	v_mfma_f32_16x16x32_bf16 v[60:63], v[72:75], v[174:177], v[60:63]
	v_mfma_f32_16x16x32_bf16 v[56:59], v[80:83], v[174:177], v[56:59]
	v_mfma_f32_16x16x32_bf16 v[44:47], v[72:75], v[196:199], v[44:47]
	v_mfma_f32_16x16x32_bf16 v[40:43], v[80:83], v[196:199], v[40:43]
	v_mfma_f32_16x16x32_bf16 v[28:31], v[72:75], v[204:207], v[28:31]
	v_mfma_f32_16x16x32_bf16 v[24:27], v[80:83], v[204:207], v[24:27]
	v_mfma_f32_16x16x32_bf16 v[12:15], v[72:75], v[212:215], v[12:15]
	v_mfma_f32_16x16x32_bf16 v[8:11], v[80:83], v[212:215], v[8:11]
	v_mfma_f32_16x16x32_bf16 v[60:63], v[76:79], v[192:195], v[60:63]
	v_mfma_f32_16x16x32_bf16 v[56:59], v[84:87], v[192:195], v[56:59]
	v_mfma_f32_16x16x32_bf16 v[44:47], v[76:79], v[200:203], v[44:47]
	v_mfma_f32_16x16x32_bf16 v[40:43], v[84:87], v[200:203], v[40:43]
	v_mfma_f32_16x16x32_bf16 v[28:31], v[76:79], v[208:211], v[28:31]
	v_mfma_f32_16x16x32_bf16 v[24:27], v[84:87], v[208:211], v[24:27]
	v_mfma_f32_16x16x32_bf16 v[12:15], v[76:79], v[230:233], v[12:15]
	v_mfma_f32_16x16x32_bf16 v[8:11], v[84:87], v[230:233], v[8:11]
	v_mfma_f32_16x16x32_bf16 v[52:55], v[154:157], v[174:177], v[52:55]
	v_mfma_f32_16x16x32_bf16 v[48:51], v[162:165], v[174:177], v[48:51]
	v_mfma_f32_16x16x32_bf16 v[36:39], v[154:157], v[196:199], v[36:39]
	v_mfma_f32_16x16x32_bf16 v[32:35], v[162:165], v[196:199], v[32:35]
	v_mfma_f32_16x16x32_bf16 v[20:23], v[154:157], v[204:207], v[20:23]
	v_mfma_f32_16x16x32_bf16 v[16:19], v[162:165], v[204:207], v[16:19]
	v_mfma_f32_16x16x32_bf16 v[4:7], v[154:157], v[212:215], v[4:7]
	v_mfma_f32_16x16x32_bf16 v[0:3], v[162:165], v[212:215], v[0:3]
	v_mfma_f32_16x16x32_bf16 v[52:55], v[158:161], v[192:195], v[52:55]
	v_mfma_f32_16x16x32_bf16 v[48:51], v[170:173], v[192:195], v[48:51]
	v_mfma_f32_16x16x32_bf16 v[36:39], v[158:161], v[200:203], v[36:39]
	v_mfma_f32_16x16x32_bf16 v[32:35], v[170:173], v[200:203], v[32:35]
	v_mfma_f32_16x16x32_bf16 v[20:23], v[158:161], v[208:211], v[20:23]
	v_mfma_f32_16x16x32_bf16 v[16:19], v[170:173], v[208:211], v[16:19]
	v_mfma_f32_16x16x32_bf16 v[4:7], v[158:161], v[230:233], v[4:7]
	v_mfma_f32_16x16x32_bf16 v[0:3], v[170:173], v[230:233], v[0:3]
	s_barrier
	s_setprio 1
	s_add_i32 s40, s40, 2
	s_add_u32 s14, s14, 0x100
	s_addc_u32 s15, s15, 0
	s_add_u32 s21, s21, 0x100
	s_addc_u32 s33, s33, 0
	s_cmp_gt_u32 s40, 13
	s_cbranch_scc0 .LBB0_503
	s_setprio 0
	s_and_b64 vcc, exec, s[48:49]
	s_cbranch_vccz .LBB0_506
	s_barrier

; #define PG8_STAGE(bufoff, gbase, voff) do { _Pragma("unroll") for (int _i = 0; _i < 2; ++_i) \
;         __builtin_amdgcn_global_load_lds((const unsigned*)((const char*)(gbase) + (voff)[_i]), (LAS unsigned*)(lds + (bufoff) + ldsw + _i * 8192), 16, 0, 0); } while (0)
; #define PG8_LDA(dst, b, h) do { _Pragma("unroll") for (int m = 0; m < 4; ++m) _Pragma("unroll") for (int k = 0; k < 2; ++k) dst[m][k] = *(const LAS bf16x8*)(lds + PG8_SA(b, h) + aoff + m * 2048 + k * 1024); } while (0)
; #define PG8_LDB(dst, b, h) do { _Pragma("unroll") for (int n = 0; n < 2; ++n) _Pragma("unroll") for (int k = 0; k < 2; ++k) dst[n][k] = *(const LAS bf16x8*)(lds + PG8_SB(b, h) + boff + n * 2048 + k * 1024); } while (0)
; #define PG8_SCHED __builtin_amdgcn_sched_barrier(0)
; template <class Epi, class Sched>
; __device__ __forceinline__ void gemm_phase(LAS unsigned char* lds, const Gemm g, const Sched& S, const Epi& E) {
;     ...
;         const int nt = cur.kc >= 0 ? nts : ntf;
;         for (int t = 0; t < nt; t += 2) {
;             const bool last = (t == nt - 2);
;             const char* a1 = cA + (size_t)(t + 1) * kstep;
;             const char* a2 = last ? nA : cA + (size_t)(t + 2) * kstep; const char* b2 = last ? nB : cB + (size_t)(t + 2) * kstep;
;             const char* a3 = a2 + kstep; const char* b3 = b2 + kstep;
;             PG8_LDB(B0, 0, 0); PG8_LDB(B1, 0, 1); PG8_SCHED; PG8_LDA(At, 0, 0); PG8_STAGE(PG8_SA(1, 1), a1 + hstep, voffA);
;     ...
; #pragma unroll
;         for (int a = 0; a < 2; ++a)
; #pragma unroll
;             for (int b = 0; b < 2; ++b)
; #pragma unroll
;                 for (int m = 0; m < 4; ++m)
; #pragma unroll
;                     for (int n = 0; n < 2; ++n) acc[a][b][m][n] = (f32x4){0.f, 0.f, 0.f, 0.f};
.LBB0_598:
	s_cmp_lt_i32 s78, 0
	s_cselect_b32 s8, s22, s23
	s_add_i32 s12, s8, -2
	s_add_u32 s6, s6, 0x80
	s_addc_u32 s7, s7, 0
	s_add_u32 s13, s14, 0x100
	v_mov_b32_e32 v0, 0
	s_mov_b32 s17, 0
	s_addc_u32 s16, s15, 0
	v_mov_b32_e32 v1, v0
	v_mov_b32_e32 v2, v0
	v_mov_b32_e32 v3, v0
	v_mov_b32_e32 v4, v0
	v_mov_b32_e32 v5, v0
	v_mov_b32_e32 v6, v0
	v_mov_b32_e32 v7, v0
	v_mov_b32_e32 v8, v0
	v_mov_b32_e32 v9, v0
	v_mov_b32_e32 v10, v0
	v_mov_b32_e32 v11, v0
	v_mov_b32_e32 v12, v0
	v_mov_b32_e32 v13, v0
	v_mov_b32_e32 v14, v0
	v_mov_b32_e32 v15, v0
	v_mov_b32_e32 v24, v0
	v_mov_b32_e32 v25, v0
	v_mov_b32_e32 v26, v0
	v_mov_b32_e32 v27, v0
	v_mov_b32_e32 v28, v0
	v_mov_b32_e32 v29, v0
	v_mov_b32_e32 v30, v0
	v_mov_b32_e32 v31, v0
	v_mov_b32_e32 v40, v0
	v_mov_b32_e32 v41, v0
	v_mov_b32_e32 v42, v0
	v_mov_b32_e32 v43, v0
	v_mov_b32_e32 v44, v0
	v_mov_b32_e32 v45, v0
	v_mov_b32_e32 v46, v0
	v_mov_b32_e32 v47, v0
	v_mov_b32_e32 v16, v0
	v_mov_b32_e32 v17, v0
	v_mov_b32_e32 v18, v0
	v_mov_b32_e32 v19, v0
	v_mov_b32_e32 v20, v0
	v_mov_b32_e32 v21, v0
	v_mov_b32_e32 v22, v0
	v_mov_b32_e32 v23, v0
	v_mov_b32_e32 v32, v0
	v_mov_b32_e32 v33, v0
	v_mov_b32_e32 v34, v0
	v_mov_b32_e32 v35, v0
	v_mov_b32_e32 v36, v0
	v_mov_b32_e32 v37, v0
	v_mov_b32_e32 v38, v0
	v_mov_b32_e32 v39, v0
	v_mov_b32_e32 v48, v0
	v_mov_b32_e32 v49, v0
	v_mov_b32_e32 v50, v0
	v_mov_b32_e32 v51, v0
	v_mov_b32_e32 v52, v0
	v_mov_b32_e32 v53, v0
	v_mov_b32_e32 v54, v0
	v_mov_b32_e32 v55, v0
	v_mov_b32_e32 v56, v0
	v_mov_b32_e32 v57, v0
	v_mov_b32_e32 v58, v0
	v_mov_b32_e32 v59, v0
	v_mov_b32_e32 v60, v0
	v_mov_b32_e32 v61, v0
	v_mov_b32_e32 v62, v0
	v_mov_b32_e32 v63, v0
	v_mov_b32_e32 v64, v0
	v_mov_b32_e32 v65, v0
	v_mov_b32_e32 v66, v0
	v_mov_b32_e32 v67, v0
	v_mov_b32_e32 v68, v0
	v_mov_b32_e32 v69, v0
	v_mov_b32_e32 v70, v0
	v_mov_b32_e32 v71, v0
	v_mov_b32_e32 v72, v0
	v_mov_b32_e32 v73, v0
	v_mov_b32_e32 v74, v0
	v_mov_b32_e32 v75, v0
	v_mov_b32_e32 v76, v0
	v_mov_b32_e32 v77, v0
	v_mov_b32_e32 v78, v0
	v_mov_b32_e32 v79, v0
	v_mov_b32_e32 v84, v0
	v_mov_b32_e32 v85, v0
	v_mov_b32_e32 v86, v0
	v_mov_b32_e32 v87, v0
	v_mov_b32_e32 v92, v0
	v_mov_b32_e32 v93, v0
	v_mov_b32_e32 v94, v0
	v_mov_b32_e32 v95, v0
	v_mov_b32_e32 v100, v0
	v_mov_b32_e32 v101, v0
	v_mov_b32_e32 v102, v0
	v_mov_b32_e32 v103, v0
	v_mov_b32_e32 v108, v0
	v_mov_b32_e32 v109, v0
	v_mov_b32_e32 v110, v0
	v_mov_b32_e32 v111, v0
	v_mov_b32_e32 v80, v0
	v_mov_b32_e32 v81, v0
	v_mov_b32_e32 v82, v0
	v_mov_b32_e32 v83, v0
	v_mov_b32_e32 v88, v0
	v_mov_b32_e32 v89, v0
	v_mov_b32_e32 v90, v0
	v_mov_b32_e32 v91, v0
	v_mov_b32_e32 v96, v0
	v_mov_b32_e32 v97, v0
	v_mov_b32_e32 v98, v0
	v_mov_b32_e32 v99, v0
	v_mov_b32_e32 v104, v0
	v_mov_b32_e32 v105, v0
	v_mov_b32_e32 v106, v0
	v_mov_b32_e32 v107, v0
	v_mov_b32_e32 v112, v0
	v_mov_b32_e32 v113, v0
	v_mov_b32_e32 v114, v0
	v_mov_b32_e32 v115, v0
	v_mov_b32_e32 v116, v0
	v_mov_b32_e32 v117, v0
	v_mov_b32_e32 v118, v0
	v_mov_b32_e32 v119, v0
	v_mov_b32_e32 v120, v0
	v_mov_b32_e32 v121, v0
	v_mov_b32_e32 v122, v0
	v_mov_b32_e32 v123, v0
	v_mov_b32_e32 v124, v0
	v_mov_b32_e32 v125, v0
	v_mov_b32_e32 v126, v0
	v_mov_b32_e32 v127, v0
	s_setprio 1
	.p2align	6
.LBB0_599:
	s_add_i32 s19, s17, 2
	s_add_u32 s14, s6, 0x80
	s_addc_u32 s15, s7, 0
	s_add_i32 s33, 0, 0x10000
	s_cmp_eq_u32 s12, s17
	s_cselect_b32 s15, s1, s15
	s_cselect_b32 s14, s0, s14
	s_cselect_b32 s43, s65, s16
	s_cselect_b32 s42, s64, s13
	s_add_i32 s17, 0, 0x14000
	v_add_u32_e32 v140, s33, v231
	v_add_u32_e32 v156, s17, v231
	s_waitcnt lgkmcnt(0)
	ds_read_b128 v[128:131], v140
	ds_read_b128 v[132:135], v140 offset:1024
	ds_read_b128 v[136:139], v140 offset:2048
	ds_read_b128 v[140:143], v140 offset:3072
	ds_read_b128 v[144:147], v156
	ds_read_b128 v[148:151], v156 offset:1024
	ds_read_b128 v[152:155], v156 offset:2048
	ds_read_b128 v[156:159], v156 offset:3072
	v_lshl_add_u64 v[214:215], s[6:7], 0, v[198:199]
	s_add_i32 m0, s29, 0xc000
	ds_read_b128 v[160:163], v232
	ds_read_b128 v[164:167], v232 offset:1024
	ds_read_b128 v[168:171], v232 offset:2048
	ds_read_b128 v[172:175], v232 offset:3072
	ds_read_b128 v[176:179], v232 offset:4096
	ds_read_b128 v[202:205], v232 offset:5120
	ds_read_b128 v[206:209], v232 offset:6144
	ds_read_b128 v[210:213], v232 offset:7168
	global_load_lds_dwordx4 v[214:215], off
	v_lshl_add_u64 v[214:215], s[6:7], 0, v[200:201]
	s_add_i32 m0, s29, 0xe000
	s_nop 0
	global_load_lds_dwordx4 v[214:215], off
	s_waitcnt vmcnt(8)
	s_waitcnt lgkmcnt(0)
	s_barrier
; #define PG8_STAGE(bufoff, gbase, voff) do { _Pragma("unroll") for (int _i = 0; _i < 2; ++_i) \
;         __builtin_amdgcn_global_load_lds((const unsigned*)((const char*)(gbase) + (voff)[_i]), (LAS unsigned*)(lds + (bufoff) + ldsw + _i * 8192), 16, 0, 0); } while (0)
; #define PG8_LDA(dst, b, h) do { _Pragma("unroll") for (int m = 0; m < 4; ++m) _Pragma("unroll") for (int k = 0; k < 2; ++k) dst[m][k] = *(const LAS bf16x8*)(lds + PG8_SA(b, h) + aoff + m * 2048 + k * 1024); } while (0)
; #define PG8_MMA(ai, bj, At, Bt) do { __builtin_amdgcn_s_setprio(1); _Pragma("unroll") for (int m = 0; m < 4; ++m) _Pragma("unroll") for (int n = 0; n < 2; ++n) _Pragma("unroll") for (int k = 0; k < 2; ++k) \
;         acc[ai][bj][m][n] = __builtin_amdgcn_mfma_f32_16x16x32_bf16(Bt[n][k], At[m][k], acc[ai][bj][m][n], 0, 0, 0); __builtin_amdgcn_s_setprio(0); } while (0)
; #define PG8_WAIT_V(n) asm volatile("s_waitcnt vmcnt(" #n ")" ::: "memory")
; #define PG8_WAIT_L(n) asm volatile("s_waitcnt lgkmcnt(" #n ")" ::: "memory")
; #define PG8_BAR __builtin_amdgcn_s_barrier()
; #define PG8_SCHED __builtin_amdgcn_sched_barrier(0)
; template <class Epi, class Sched>
; __device__ __forceinline__ void gemm_phase(LAS unsigned char* lds, const Gemm g, const Sched& S, const Epi& E) {
;     ...
;             PG8_WAIT_V(8); PG8_WAIT_L(0); PG8_BAR; PG8_MMA(0, 0, At, B0); PG8_MMA(0, 1, At, B1); PG8_BAR; PG8_SCHED;
;             PG8_LDA(At, 0, 1); PG8_STAGE(PG8_SB(0, 0), b2, voffB); PG8_STAGE(PG8_SB(0, 1), b2 + hstep, voffB); PG8_STAGE(PG8_SA(0, 0), a2, voffA);
;             PG8_WAIT_V(8); PG8_WAIT_L(0); PG8_BAR; PG8_MMA(1, 0, At, B0); PG8_MMA(1, 1, At, B1); PG8_BAR; PG8_SCHED;
	s_setprio 0
	s_waitcnt lgkmcnt(0)
	v_mfma_f32_16x16x32_bf16 v[124:127], v[128:131], v[160:163], v[124:127]
	v_mfma_f32_16x16x32_bf16 v[120:123], v[136:139], v[160:163], v[120:123]
	v_mfma_f32_16x16x32_bf16 v[116:119], v[128:131], v[168:171], v[116:119]
	v_mfma_f32_16x16x32_bf16 v[112:115], v[136:139], v[168:171], v[112:115]
	v_mfma_f32_16x16x32_bf16 v[104:107], v[128:131], v[176:179], v[104:107]
	v_mfma_f32_16x16x32_bf16 v[96:99], v[136:139], v[176:179], v[96:99]
	v_mfma_f32_16x16x32_bf16 v[88:91], v[128:131], v[206:209], v[88:91]
	v_mfma_f32_16x16x32_bf16 v[80:83], v[136:139], v[206:209], v[80:83]
	v_mfma_f32_16x16x32_bf16 v[124:127], v[132:135], v[164:167], v[124:127]
	v_mfma_f32_16x16x32_bf16 v[120:123], v[140:143], v[164:167], v[120:123]
	v_mfma_f32_16x16x32_bf16 v[116:119], v[132:135], v[172:175], v[116:119]
	v_mfma_f32_16x16x32_bf16 v[112:115], v[140:143], v[172:175], v[112:115]
	v_mfma_f32_16x16x32_bf16 v[104:107], v[132:135], v[202:205], v[104:107]
	v_mfma_f32_16x16x32_bf16 v[96:99], v[140:143], v[202:205], v[96:99]
	v_mfma_f32_16x16x32_bf16 v[88:91], v[132:135], v[210:213], v[88:91]
	v_mfma_f32_16x16x32_bf16 v[80:83], v[140:143], v[210:213], v[80:83]
	v_mfma_f32_16x16x32_bf16 v[108:111], v[144:147], v[160:163], v[108:111]
	v_mfma_f32_16x16x32_bf16 v[100:103], v[152:155], v[160:163], v[100:103]
	v_mfma_f32_16x16x32_bf16 v[92:95], v[144:147], v[168:171], v[92:95]
	v_mfma_f32_16x16x32_bf16 v[84:87], v[152:155], v[168:171], v[84:87]
	v_mfma_f32_16x16x32_bf16 v[76:79], v[144:147], v[176:179], v[76:79]
	v_mfma_f32_16x16x32_bf16 v[72:75], v[152:155], v[176:179], v[72:75]
	v_mfma_f32_16x16x32_bf16 v[68:71], v[144:147], v[206:209], v[68:71]
	v_mfma_f32_16x16x32_bf16 v[64:67], v[152:155], v[206:209], v[64:67]
	v_mfma_f32_16x16x32_bf16 v[108:111], v[148:151], v[164:167], v[108:111]
	v_mfma_f32_16x16x32_bf16 v[100:103], v[156:159], v[164:167], v[100:103]
	v_mfma_f32_16x16x32_bf16 v[92:95], v[148:151], v[172:175], v[92:95]
	v_mfma_f32_16x16x32_bf16 v[84:87], v[156:159], v[172:175], v[84:87]
	v_mfma_f32_16x16x32_bf16 v[76:79], v[148:151], v[202:205], v[76:79]
	v_mfma_f32_16x16x32_bf16 v[72:75], v[156:159], v[202:205], v[72:75]
	v_mfma_f32_16x16x32_bf16 v[68:71], v[148:151], v[210:213], v[68:71]
	v_mfma_f32_16x16x32_bf16 v[64:67], v[156:159], v[210:213], v[64:67]
	s_barrier
	s_setprio 1
	s_add_i32 s33, s33, s28
	v_lshl_add_u64 v[214:215], s[42:43], 0, v[184:185]
	s_mov_b32 m0, s33
	ds_read_b128 v[160:163], v232 offset:16384
	ds_read_b128 v[164:167], v232 offset:17408
	ds_read_b128 v[168:171], v232 offset:18432
	ds_read_b128 v[172:175], v232 offset:19456
	ds_read_b128 v[176:179], v232 offset:20480
	ds_read_b128 v[202:205], v232 offset:21504
	ds_read_b128 v[206:209], v232 offset:22528
	ds_read_b128 v[210:213], v232 offset:23552
	global_load_lds_dwordx4 v[214:215], off
	s_add_i32 m0, s33, 0x2000
	v_lshl_add_u64 v[216:217], s[42:43], 0, v[196:197]
	s_add_u32 s42, s42, s54
	s_addc_u32 s43, s43, 0
	s_add_i32 s17, s17, s28
	global_load_lds_dwordx4 v[216:217], off
	v_lshl_add_u64 v[234:235], s[42:43], 0, v[184:185]
	s_mov_b32 m0, s17
	v_lshl_add_u64 v[236:237], s[42:43], 0, v[196:197]
	global_load_lds_dwordx4 v[234:235], off
	s_add_i32 m0, s17, 0x2000
	v_lshl_add_u64 v[238:239], s[14:15], 0, v[192:193]
	global_load_lds_dwordx4 v[236:237], off
	s_mov_b32 m0, s29
	v_lshl_add_u64 v[240:241], s[14:15], 0, v[194:195]
	global_load_lds_dwordx4 v[238:239], off
	s_mov_b32 m0, s30
	s_nop 0
	global_load_lds_dwordx4 v[240:241], off
	s_waitcnt vmcnt(8)
	s_waitcnt lgkmcnt(0)
	s_barrier
	s_setprio 0
	s_waitcnt lgkmcnt(0)
	v_mfma_f32_16x16x32_bf16 v[60:63], v[128:131], v[160:163], v[60:63]
	v_mfma_f32_16x16x32_bf16 v[56:59], v[136:139], v[160:163], v[56:59]
	v_mfma_f32_16x16x32_bf16 v[52:55], v[128:131], v[168:171], v[52:55]
	v_mfma_f32_16x16x32_bf16 v[48:51], v[136:139], v[168:171], v[48:51]
	v_mfma_f32_16x16x32_bf16 v[36:39], v[128:131], v[176:179], v[36:39]
	v_mfma_f32_16x16x32_bf16 v[32:35], v[136:139], v[176:179], v[32:35]
	v_mfma_f32_16x16x32_bf16 v[20:23], v[128:131], v[206:209], v[20:23]
	v_mfma_f32_16x16x32_bf16 v[16:19], v[136:139], v[206:209], v[16:19]
	v_mfma_f32_16x16x32_bf16 v[60:63], v[132:135], v[164:167], v[60:63]
	v_mfma_f32_16x16x32_bf16 v[56:59], v[140:143], v[164:167], v[56:59]
	v_mfma_f32_16x16x32_bf16 v[52:55], v[132:135], v[172:175], v[52:55]
	v_mfma_f32_16x16x32_bf16 v[48:51], v[140:143], v[172:175], v[48:51]
	v_mfma_f32_16x16x32_bf16 v[36:39], v[132:135], v[202:205], v[36:39]
	v_mfma_f32_16x16x32_bf16 v[32:35], v[140:143], v[202:205], v[32:35]
	v_mfma_f32_16x16x32_bf16 v[20:23], v[132:135], v[210:213], v[20:23]
	v_mfma_f32_16x16x32_bf16 v[16:19], v[140:143], v[210:213], v[16:19]
	v_mfma_f32_16x16x32_bf16 v[44:47], v[144:147], v[160:163], v[44:47]
	v_mfma_f32_16x16x32_bf16 v[40:43], v[152:155], v[160:163], v[40:43]
	v_mfma_f32_16x16x32_bf16 v[28:31], v[144:147], v[168:171], v[28:31]
	v_mfma_f32_16x16x32_bf16 v[24:27], v[152:155], v[168:171], v[24:27]
	v_mfma_f32_16x16x32_bf16 v[12:15], v[144:147], v[176:179], v[12:15]
	v_mfma_f32_16x16x32_bf16 v[8:11], v[152:155], v[176:179], v[8:11]
	v_mfma_f32_16x16x32_bf16 v[4:7], v[144:147], v[206:209], v[4:7]
	v_mfma_f32_16x16x32_bf16 v[0:3], v[152:155], v[206:209], v[0:3]
	v_mfma_f32_16x16x32_bf16 v[44:47], v[148:151], v[164:167], v[44:47]
	v_mfma_f32_16x16x32_bf16 v[40:43], v[156:159], v[164:167], v[40:43]
	v_mfma_f32_16x16x32_bf16 v[28:31], v[148:151], v[172:175], v[28:31]
	v_mfma_f32_16x16x32_bf16 v[24:27], v[156:159], v[172:175], v[24:27]
	v_mfma_f32_16x16x32_bf16 v[12:15], v[148:151], v[202:205], v[12:15]
	v_mfma_f32_16x16x32_bf16 v[8:11], v[156:159], v[202:205], v[8:11]
	v_mfma_f32_16x16x32_bf16 v[4:7], v[148:151], v[210:213], v[4:7]
	v_mfma_f32_16x16x32_bf16 v[0:3], v[156:159], v[210:213], v[0:3]
	s_barrier
; #define PG8_STAGE(bufoff, gbase, voff) do { _Pragma("unroll") for (int _i = 0; _i < 2; ++_i) \
;         __builtin_amdgcn_global_load_lds((const unsigned*)((const char*)(gbase) + (voff)[_i]), (LAS unsigned*)(lds + (bufoff) + ldsw + _i * 8192), 16, 0, 0); } while (0)
; #define PG8_LDA(dst, b, h) do { _Pragma("unroll") for (int m = 0; m < 4; ++m) _Pragma("unroll") for (int k = 0; k < 2; ++k) dst[m][k] = *(const LAS bf16x8*)(lds + PG8_SA(b, h) + aoff + m * 2048 + k * 1024); } while (0)
; #define PG8_LDB(dst, b, h) do { _Pragma("unroll") for (int n = 0; n < 2; ++n) _Pragma("unroll") for (int k = 0; k < 2; ++k) dst[n][k] = *(const LAS bf16x8*)(lds + PG8_SB(b, h) + boff + n * 2048 + k * 1024); } while (0)
; #define PG8_MMA(ai, bj, At, Bt) do { __builtin_amdgcn_s_setprio(1); _Pragma("unroll") for (int m = 0; m < 4; ++m) _Pragma("unroll") for (int n = 0; n < 2; ++n) _Pragma("unroll") for (int k = 0; k < 2; ++k) \
;         acc[ai][bj][m][n] = __builtin_amdgcn_mfma_f32_16x16x32_bf16(Bt[n][k], At[m][k], acc[ai][bj][m][n], 0, 0, 0); __builtin_amdgcn_s_setprio(0); } while (0)
; #define PG8_WAIT_V(n) asm volatile("s_waitcnt vmcnt(" #n ")" ::: "memory")
; #define PG8_WAIT_L(n) asm volatile("s_waitcnt lgkmcnt(" #n ")" ::: "memory")
; #define PG8_BAR __builtin_amdgcn_s_barrier()
; #define PG8_SCHED __builtin_amdgcn_sched_barrier(0)
; template <class Epi, class Sched>
; __device__ __forceinline__ void gemm_phase(LAS unsigned char* lds, const Gemm g, const Sched& S, const Epi& E) {
;     ...
;             PG8_LDB(B0, 1, 0); PG8_LDB(B1, 1, 1); PG8_SCHED; PG8_LDA(At, 1, 0); PG8_STAGE(PG8_SA(0, 1), a2 + hstep, voffA);
;             PG8_WAIT_V(8); PG8_WAIT_L(0); PG8_BAR; PG8_MMA(0, 0, At, B0); PG8_MMA(0, 1, At, B1); PG8_BAR; PG8_SCHED;
	s_setprio 1
	s_add_i32 s17, 0, 0x18000
	s_add_i32 s33, 0, 0x1c000
	v_add_u32_e32 v140, s17, v231
	v_add_u32_e32 v156, s33, v231
	ds_read_b128 v[128:131], v140
	ds_read_b128 v[132:135], v140 offset:1024
	ds_read_b128 v[136:139], v140 offset:2048
	ds_read_b128 v[140:143], v140 offset:3072
	ds_read_b128 v[144:147], v156
	ds_read_b128 v[148:151], v156 offset:1024
	ds_read_b128 v[152:155], v156 offset:2048
	ds_read_b128 v[156:159], v156 offset:3072
	s_add_u32 s14, s14, s54
	s_addc_u32 s15, s15, 0
	s_mov_b32 m0, s31
	v_lshl_add_u64 v[242:243], s[14:15], 0, v[192:193]
	ds_read_b128 v[160:163], v232 offset:32768
	ds_read_b128 v[164:167], v232 offset:33792
	ds_read_b128 v[168:171], v232 offset:34816
	ds_read_b128 v[172:175], v232 offset:35840
	ds_read_b128 v[176:179], v232 offset:36864
	ds_read_b128 v[202:205], v232 offset:37888
	ds_read_b128 v[206:209], v232 offset:38912
	ds_read_b128 v[210:213], v232 offset:39936
	global_load_lds_dwordx4 v[242:243], off
	v_lshl_add_u64 v[242:243], s[14:15], 0, v[194:195]
	s_mov_b32 m0, s34
	s_nop 0
	global_load_lds_dwordx4 v[242:243], off
	s_waitcnt vmcnt(8)
	s_waitcnt lgkmcnt(0)
	s_barrier
	s_setprio 0
	s_waitcnt lgkmcnt(0)
	v_mfma_f32_16x16x32_bf16 v[124:127], v[128:131], v[160:163], v[124:127]
	v_mfma_f32_16x16x32_bf16 v[120:123], v[136:139], v[160:163], v[120:123]
	v_mfma_f32_16x16x32_bf16 v[116:119], v[128:131], v[168:171], v[116:119]
	v_mfma_f32_16x16x32_bf16 v[112:115], v[136:139], v[168:171], v[112:115]
	v_mfma_f32_16x16x32_bf16 v[104:107], v[128:131], v[176:179], v[104:107]
	v_mfma_f32_16x16x32_bf16 v[96:99], v[136:139], v[176:179], v[96:99]
	v_mfma_f32_16x16x32_bf16 v[88:91], v[128:131], v[206:209], v[88:91]
	v_mfma_f32_16x16x32_bf16 v[80:83], v[136:139], v[206:209], v[80:83]
	v_mfma_f32_16x16x32_bf16 v[124:127], v[132:135], v[164:167], v[124:127]
	v_mfma_f32_16x16x32_bf16 v[120:123], v[140:143], v[164:167], v[120:123]
	v_mfma_f32_16x16x32_bf16 v[116:119], v[132:135], v[172:175], v[116:119]
	v_mfma_f32_16x16x32_bf16 v[112:115], v[140:143], v[172:175], v[112:115]
	v_mfma_f32_16x16x32_bf16 v[104:107], v[132:135], v[202:205], v[104:107]
	v_mfma_f32_16x16x32_bf16 v[96:99], v[140:143], v[202:205], v[96:99]
	v_mfma_f32_16x16x32_bf16 v[88:91], v[132:135], v[210:213], v[88:91]
	v_mfma_f32_16x16x32_bf16 v[80:83], v[140:143], v[210:213], v[80:83]
	v_mfma_f32_16x16x32_bf16 v[108:111], v[144:147], v[160:163], v[108:111]
	v_mfma_f32_16x16x32_bf16 v[100:103], v[152:155], v[160:163], v[100:103]
	v_mfma_f32_16x16x32_bf16 v[92:95], v[144:147], v[168:171], v[92:95]
	v_mfma_f32_16x16x32_bf16 v[84:87], v[152:155], v[168:171], v[84:87]
	v_mfma_f32_16x16x32_bf16 v[76:79], v[144:147], v[176:179], v[76:79]
	v_mfma_f32_16x16x32_bf16 v[72:75], v[152:155], v[176:179], v[72:75]
	v_mfma_f32_16x16x32_bf16 v[68:71], v[144:147], v[206:209], v[68:71]
	v_mfma_f32_16x16x32_bf16 v[64:67], v[152:155], v[206:209], v[64:67]
	v_mfma_f32_16x16x32_bf16 v[108:111], v[148:151], v[164:167], v[108:111]
	v_mfma_f32_16x16x32_bf16 v[100:103], v[156:159], v[164:167], v[100:103]
	v_mfma_f32_16x16x32_bf16 v[92:95], v[148:151], v[172:175], v[92:95]
	v_mfma_f32_16x16x32_bf16 v[84:87], v[156:159], v[172:175], v[84:87]
	v_mfma_f32_16x16x32_bf16 v[76:79], v[148:151], v[202:205], v[76:79]
	v_mfma_f32_16x16x32_bf16 v[72:75], v[156:159], v[202:205], v[72:75]
	v_mfma_f32_16x16x32_bf16 v[68:71], v[148:151], v[210:213], v[68:71]
	v_mfma_f32_16x16x32_bf16 v[64:67], v[156:159], v[210:213], v[64:67]
	s_barrier
; #define PG8_STAGE(bufoff, gbase, voff) do { _Pragma("unroll") for (int _i = 0; _i < 2; ++_i) \
;         __builtin_amdgcn_global_load_lds((const unsigned*)((const char*)(gbase) + (voff)[_i]), (LAS unsigned*)(lds + (bufoff) + ldsw + _i * 8192), 16, 0, 0); } while (0)
; #define PG8_LDA(dst, b, h) do { _Pragma("unroll") for (int m = 0; m < 4; ++m) _Pragma("unroll") for (int k = 0; k < 2; ++k) dst[m][k] = *(const LAS bf16x8*)(lds + PG8_SA(b, h) + aoff + m * 2048 + k * 1024); } while (0)
; #define PG8_MMA(ai, bj, At, Bt) do { __builtin_amdgcn_s_setprio(1); _Pragma("unroll") for (int m = 0; m < 4; ++m) _Pragma("unroll") for (int n = 0; n < 2; ++n) _Pragma("unroll") for (int k = 0; k < 2; ++k) \
;         acc[ai][bj][m][n] = __builtin_amdgcn_mfma_f32_16x16x32_bf16(Bt[n][k], At[m][k], acc[ai][bj][m][n], 0, 0, 0); __builtin_amdgcn_s_setprio(0); } while (0)
; #define PG8_WAIT_V(n) asm volatile("s_waitcnt vmcnt(" #n ")" ::: "memory")
; #define PG8_WAIT_L(n) asm volatile("s_waitcnt lgkmcnt(" #n ")" ::: "memory")
; #define PG8_BAR __builtin_amdgcn_s_barrier()
; #define PG8_SCHED __builtin_amdgcn_sched_barrier(0)
; template <class Epi, class Sched>
; __device__ __forceinline__ void gemm_phase(LAS unsigned char* lds, const Gemm g, const Sched& S, const Epi& E) {
;     ...
;             PG8_LDA(At, 1, 1); PG8_STAGE(PG8_SB(1, 0), b3, voffB); PG8_STAGE(PG8_SB(1, 1), b3 + hstep, voffB); PG8_STAGE(PG8_SA(1, 0), a3, voffA);
;             PG8_WAIT_V(8); PG8_WAIT_L(0); PG8_BAR; PG8_MMA(1, 0, At, B0); PG8_MMA(1, 1, At, B1); PG8_BAR; PG8_SCHED;
;         }
;         if (wr == 0) PG8_BAR;
	s_setprio 1
	s_add_i32 s14, s17, s28
	v_lshl_add_u64 v[214:215], v[214:215], 0, s[84:85]
	s_mov_b32 m0, s14
	ds_read_b128 v[160:163], v232 offset:49152
	ds_read_b128 v[164:167], v232 offset:50176
	ds_read_b128 v[168:171], v232 offset:51200
	ds_read_b128 v[172:175], v232 offset:52224
	ds_read_b128 v[176:179], v232 offset:53248
	ds_read_b128 v[202:205], v232 offset:54272
	ds_read_b128 v[206:209], v232 offset:55296
	ds_read_b128 v[210:213], v232 offset:56320
	global_load_lds_dwordx4 v[214:215], off
	v_lshl_add_u64 v[214:215], v[216:217], 0, s[84:85]
	s_add_i32 m0, s14, 0x2000
	s_add_i32 s14, s33, s28
	global_load_lds_dwordx4 v[214:215], off
	v_lshl_add_u64 v[214:215], v[234:235], 0, s[84:85]
	s_mov_b32 m0, s14
	s_nop 0
	global_load_lds_dwordx4 v[214:215], off
	v_lshl_add_u64 v[214:215], v[236:237], 0, s[84:85]
	s_add_i32 m0, s14, 0x2000
	s_nop 0
	global_load_lds_dwordx4 v[214:215], off
	v_lshl_add_u64 v[214:215], v[238:239], 0, s[84:85]
	s_mov_b32 m0, s66
	s_nop 0
	global_load_lds_dwordx4 v[214:215], off
	v_lshl_add_u64 v[214:215], v[240:241], 0, s[84:85]
	s_mov_b32 m0, s67
	s_nop 0
	global_load_lds_dwordx4 v[214:215], off
	s_waitcnt vmcnt(8)
	s_waitcnt lgkmcnt(0)
	s_barrier
	s_setprio 0
	s_waitcnt lgkmcnt(0)
	v_mfma_f32_16x16x32_bf16 v[60:63], v[128:131], v[160:163], v[60:63]
	v_mfma_f32_16x16x32_bf16 v[56:59], v[136:139], v[160:163], v[56:59]
	v_mfma_f32_16x16x32_bf16 v[52:55], v[128:131], v[168:171], v[52:55]
	v_mfma_f32_16x16x32_bf16 v[48:51], v[136:139], v[168:171], v[48:51]
	v_mfma_f32_16x16x32_bf16 v[36:39], v[128:131], v[176:179], v[36:39]
	v_mfma_f32_16x16x32_bf16 v[32:35], v[136:139], v[176:179], v[32:35]
	v_mfma_f32_16x16x32_bf16 v[20:23], v[128:131], v[206:209], v[20:23]
	v_mfma_f32_16x16x32_bf16 v[16:19], v[136:139], v[206:209], v[16:19]
	v_mfma_f32_16x16x32_bf16 v[60:63], v[132:135], v[164:167], v[60:63]
	v_mfma_f32_16x16x32_bf16 v[56:59], v[140:143], v[164:167], v[56:59]
	v_mfma_f32_16x16x32_bf16 v[52:55], v[132:135], v[172:175], v[52:55]
	v_mfma_f32_16x16x32_bf16 v[48:51], v[140:143], v[172:175], v[48:51]
	v_mfma_f32_16x16x32_bf16 v[36:39], v[132:135], v[202:205], v[36:39]
	v_mfma_f32_16x16x32_bf16 v[32:35], v[140:143], v[202:205], v[32:35]
	v_mfma_f32_16x16x32_bf16 v[20:23], v[132:135], v[210:213], v[20:23]
	v_mfma_f32_16x16x32_bf16 v[16:19], v[140:143], v[210:213], v[16:19]
	v_mfma_f32_16x16x32_bf16 v[44:47], v[144:147], v[160:163], v[44:47]
	v_mfma_f32_16x16x32_bf16 v[40:43], v[152:155], v[160:163], v[40:43]
	v_mfma_f32_16x16x32_bf16 v[28:31], v[144:147], v[168:171], v[28:31]
	v_mfma_f32_16x16x32_bf16 v[24:27], v[152:155], v[168:171], v[24:27]
	v_mfma_f32_16x16x32_bf16 v[12:15], v[144:147], v[176:179], v[12:15]
	v_mfma_f32_16x16x32_bf16 v[8:11], v[152:155], v[176:179], v[8:11]
	v_mfma_f32_16x16x32_bf16 v[4:7], v[144:147], v[206:209], v[4:7]
	v_mfma_f32_16x16x32_bf16 v[0:3], v[152:155], v[206:209], v[0:3]
	v_mfma_f32_16x16x32_bf16 v[44:47], v[148:151], v[164:167], v[44:47]
	v_mfma_f32_16x16x32_bf16 v[40:43], v[156:159], v[164:167], v[40:43]
	v_mfma_f32_16x16x32_bf16 v[28:31], v[148:151], v[172:175], v[28:31]
	v_mfma_f32_16x16x32_bf16 v[24:27], v[156:159], v[172:175], v[24:27]
	v_mfma_f32_16x16x32_bf16 v[12:15], v[148:151], v[202:205], v[12:15]
	v_mfma_f32_16x16x32_bf16 v[8:11], v[156:159], v[202:205], v[8:11]
	v_mfma_f32_16x16x32_bf16 v[4:7], v[148:151], v[210:213], v[4:7]
	v_mfma_f32_16x16x32_bf16 v[0:3], v[156:159], v[210:213], v[0:3]
	s_barrier
	s_setprio 1
	s_add_u32 s6, s6, 0x100
	s_addc_u32 s7, s7, 0
	s_add_u32 s13, s13, 0x100
	s_addc_u32 s16, s16, 0
	s_cmp_ge_u32 s19, s8
	s_mov_b32 s17, s19
	s_cbranch_scc0 .LBB0_599
	s_setprio 0
	s_and_b64 vcc, exec, s[62:63]
	s_cbranch_vccz .LBB0_602
	s_barrier

; #define PG8_STAGE(bufoff, gbase, voff) do { _Pragma("unroll") for (int _i = 0; _i < 2; ++_i) \
;         __builtin_amdgcn_global_load_lds((const unsigned*)((const char*)(gbase) + (voff)[_i]), (LAS unsigned*)(lds + (bufoff) + ldsw + _i * 8192), 16, 0, 0); } while (0)
; #define PG8_LDA(dst, b, h) do { _Pragma("unroll") for (int m = 0; m < 4; ++m) _Pragma("unroll") for (int k = 0; k < 2; ++k) dst[m][k] = *(const LAS bf16x8*)(lds + PG8_SA(b, h) + aoff + m * 2048 + k * 1024); } while (0)
; #define PG8_LDB(dst, b, h) do { _Pragma("unroll") for (int n = 0; n < 2; ++n) _Pragma("unroll") for (int k = 0; k < 2; ++k) dst[n][k] = *(const LAS bf16x8*)(lds + PG8_SB(b, h) + boff + n * 2048 + k * 1024); } while (0)
; #define PG8_SCHED __builtin_amdgcn_sched_barrier(0)
; template <class Epi, class Sched>
; __device__ __forceinline__ void gemm_phase(LAS unsigned char* lds, const Gemm g, const Sched& S, const Epi& E) {
;     ...
;         const bool has_next = S.next(ui + 1, nxt);
;         const size_t nko = (has_next && nxt.kc > 0) ? (size_t)nxt.kc * nts * kstep : 0;
;         const char* nA = has_next ? (const char*)g.A + (size_t)nxt.pm * tstep + nko : cA; const char* nB = has_next ? (const char*)g.Bt + (size_t)nxt.pn * tstep + nko : cB;
;         const int nt = cur.kc >= 0 ? nts : ntf;
;         for (int t = 0; t < nt; t += 2) {
;             const bool last = (t == nt - 2);
;             const char* a1 = cA + (size_t)(t + 1) * kstep;
;             const char* a2 = last ? nA : cA + (size_t)(t + 2) * kstep; const char* b2 = last ? nB : cB + (size_t)(t + 2) * kstep;
;             const char* a3 = a2 + kstep; const char* b3 = b2 + kstep;
;             PG8_LDB(B0, 0, 0); PG8_LDB(B1, 0, 1); PG8_SCHED; PG8_LDA(At, 0, 0); PG8_STAGE(PG8_SA(1, 1), a1 + hstep, voffA);
;     ...
; #pragma unroll
;         for (int a = 0; a < 2; ++a)
; #pragma unroll
;             for (int b = 0; b < 2; ++b)
; #pragma unroll
;                 for (int m = 0; m < 4; ++m)
; #pragma unroll
;                     for (int n = 0; n < 2; ++n) acc[a][b][m][n] = (f32x4){0.f, 0.f, 0.f, 0.f};
.LBB0_743:
	s_ashr_i32 s15, s14, 31
	s_lshl_b64 s[18:19], s[14:15], 19
	s_add_u32 s18, s92, s18
	s_addc_u32 s19, s93, s19
	s_and_b64 s[20:21], s[38:39], exec
	s_cselect_b32 s15, s19, s23
	s_cselect_b32 s44, s18, s22
	s_ashr_i32 s17, s16, 31
	s_lshl_b64 s[20:21], s[16:17], 19
	s_add_u32 s20, s9, s20
	s_addc_u32 s21, s12, s21
	s_and_b64 s[26:27], s[38:39], exec
	s_cselect_b32 s17, s21, s25
	s_cselect_b32 s45, s20, s24
	s_add_u32 s22, s22, 0x40080
	s_addc_u32 s23, s23, 0
	s_add_u32 s46, s24, 0x100
	v_mov_b32_e32 v4, 0
	s_addc_u32 s47, s25, 0
	s_mov_b32 s48, -2
	v_mov_b32_e32 v5, v4
	v_mov_b32_e32 v6, v4
	v_mov_b32_e32 v7, v4
	v_mov_b32_e32 v0, v4
	v_mov_b32_e32 v1, v4
	v_mov_b32_e32 v2, v4
	v_mov_b32_e32 v3, v4
	v_mov_b32_e32 v20, v4
	v_mov_b32_e32 v21, v4
	v_mov_b32_e32 v22, v4
	v_mov_b32_e32 v23, v4
	v_mov_b32_e32 v16, v4
	v_mov_b32_e32 v17, v4
	v_mov_b32_e32 v18, v4
	v_mov_b32_e32 v19, v4
	v_mov_b32_e32 v36, v4
	v_mov_b32_e32 v37, v4
	v_mov_b32_e32 v38, v4
	v_mov_b32_e32 v39, v4
	v_mov_b32_e32 v32, v4
	v_mov_b32_e32 v33, v4
	v_mov_b32_e32 v34, v4
	v_mov_b32_e32 v35, v4
	v_mov_b32_e32 v52, v4
	v_mov_b32_e32 v53, v4
	v_mov_b32_e32 v54, v4
	v_mov_b32_e32 v55, v4
	v_mov_b32_e32 v48, v4
	v_mov_b32_e32 v49, v4
	v_mov_b32_e32 v50, v4
	v_mov_b32_e32 v51, v4
	v_mov_b32_e32 v8, v4
	v_mov_b32_e32 v9, v4
	v_mov_b32_e32 v10, v4
	v_mov_b32_e32 v11, v4
	v_mov_b32_e32 v12, v4
	v_mov_b32_e32 v13, v4
	v_mov_b32_e32 v14, v4
	v_mov_b32_e32 v15, v4
	v_mov_b32_e32 v24, v4
	v_mov_b32_e32 v25, v4
	v_mov_b32_e32 v26, v4
	v_mov_b32_e32 v27, v4
	v_mov_b32_e32 v28, v4
	v_mov_b32_e32 v29, v4
	v_mov_b32_e32 v30, v4
	v_mov_b32_e32 v31, v4
	v_mov_b32_e32 v40, v4
	v_mov_b32_e32 v41, v4
	v_mov_b32_e32 v42, v4
	v_mov_b32_e32 v43, v4
	v_mov_b32_e32 v44, v4
	v_mov_b32_e32 v45, v4
	v_mov_b32_e32 v46, v4
	v_mov_b32_e32 v47, v4
	v_mov_b32_e32 v56, v4
	v_mov_b32_e32 v57, v4
	v_mov_b32_e32 v58, v4
	v_mov_b32_e32 v59, v4
	v_mov_b32_e32 v60, v4
	v_mov_b32_e32 v61, v4
	v_mov_b32_e32 v62, v4
	v_mov_b32_e32 v63, v4
	v_mov_b32_e32 v68, v4
	v_mov_b32_e32 v69, v4
	v_mov_b32_e32 v70, v4
	v_mov_b32_e32 v71, v4
	v_mov_b32_e32 v64, v4
	v_mov_b32_e32 v65, v4
	v_mov_b32_e32 v66, v4
	v_mov_b32_e32 v67, v4
	v_mov_b32_e32 v84, v4
	v_mov_b32_e32 v85, v4
	v_mov_b32_e32 v86, v4
	v_mov_b32_e32 v87, v4
	v_mov_b32_e32 v80, v4
	v_mov_b32_e32 v81, v4
	v_mov_b32_e32 v82, v4
	v_mov_b32_e32 v83, v4
	v_mov_b32_e32 v100, v4
	v_mov_b32_e32 v101, v4
	v_mov_b32_e32 v102, v4
	v_mov_b32_e32 v103, v4
	v_mov_b32_e32 v96, v4
	v_mov_b32_e32 v97, v4
	v_mov_b32_e32 v98, v4
	v_mov_b32_e32 v99, v4
	v_mov_b32_e32 v116, v4
	v_mov_b32_e32 v117, v4
	v_mov_b32_e32 v118, v4
	v_mov_b32_e32 v119, v4
	v_mov_b32_e32 v112, v4
	v_mov_b32_e32 v113, v4
	v_mov_b32_e32 v114, v4
	v_mov_b32_e32 v115, v4
	v_mov_b32_e32 v72, v4
	v_mov_b32_e32 v73, v4
	v_mov_b32_e32 v74, v4
	v_mov_b32_e32 v75, v4
	v_mov_b32_e32 v76, v4
	v_mov_b32_e32 v77, v4
	v_mov_b32_e32 v78, v4
	v_mov_b32_e32 v79, v4
	v_mov_b32_e32 v88, v4
	v_mov_b32_e32 v89, v4
	v_mov_b32_e32 v90, v4
	v_mov_b32_e32 v91, v4
	v_mov_b32_e32 v92, v4
	v_mov_b32_e32 v93, v4
	v_mov_b32_e32 v94, v4
	v_mov_b32_e32 v95, v4
	v_mov_b32_e32 v104, v4
	v_mov_b32_e32 v105, v4
	v_mov_b32_e32 v106, v4
	v_mov_b32_e32 v107, v4
	v_mov_b32_e32 v108, v4
	v_mov_b32_e32 v109, v4
	v_mov_b32_e32 v110, v4
	v_mov_b32_e32 v111, v4
	v_mov_b32_e32 v120, v4
	v_mov_b32_e32 v121, v4
	v_mov_b32_e32 v122, v4
	v_mov_b32_e32 v123, v4
	v_mov_b32_e32 v124, v4
	v_mov_b32_e32 v125, v4
	v_mov_b32_e32 v126, v4
	v_mov_b32_e32 v127, v4
	s_setprio 1
	.p2align	6
.LBB0_744:
	s_add_u32 s24, s22, 0xfffc0080
	s_addc_u32 s25, s23, -1
	s_add_i32 s49, 0, 0x10000
	s_cmp_eq_u32 s48, 12
	s_cselect_b32 s27, s15, s25
	s_cselect_b32 s26, s44, s24
	s_cselect_b32 s25, s17, s47
	s_cselect_b32 s24, s45, s46
	s_add_i32 s52, 0, 0x14000
	v_add_u32_e32 v140, s49, v162
	v_add_u32_e32 v158, s52, v162
	ds_read_b128 v[128:131], v140
	ds_read_b128 v[132:135], v140 offset:1024
	ds_read_b128 v[136:139], v140 offset:2048
	ds_read_b128 v[140:143], v140 offset:3072
	ds_read_b128 v[154:157], v158
	ds_read_b128 v[164:167], v158 offset:1024
	ds_read_b128 v[168:171], v158 offset:2048
	ds_read_b128 v[172:175], v158 offset:3072
	v_lshl_add_u64 v[158:159], s[22:23], 0, v[150:151]
	s_add_i32 m0, s28, 0xc000
	ds_read_b128 v[176:179], v163
	ds_read_b128 v[192:195], v163 offset:1024
	ds_read_b128 v[196:199], v163 offset:2048
	ds_read_b128 v[200:203], v163 offset:3072
	ds_read_b128 v[204:207], v163 offset:4096
	ds_read_b128 v[208:211], v163 offset:5120
	ds_read_b128 v[212:215], v163 offset:6144
	ds_read_b128 v[230:233], v163 offset:7168
	global_load_lds_dwordx4 v[158:159], off
	v_lshl_add_u64 v[158:159], s[22:23], 0, v[152:153]
	s_add_i32 m0, s28, 0xe000
	s_nop 0
	global_load_lds_dwordx4 v[158:159], off
	s_waitcnt vmcnt(8)
	s_waitcnt lgkmcnt(0)
	s_barrier
; #define PG8_STAGE(bufoff, gbase, voff) do { _Pragma("unroll") for (int _i = 0; _i < 2; ++_i) \
;         __builtin_amdgcn_global_load_lds((const unsigned*)((const char*)(gbase) + (voff)[_i]), (LAS unsigned*)(lds + (bufoff) + ldsw + _i * 8192), 16, 0, 0); } while (0)
; #define PG8_LDA(dst, b, h) do { _Pragma("unroll") for (int m = 0; m < 4; ++m) _Pragma("unroll") for (int k = 0; k < 2; ++k) dst[m][k] = *(const LAS bf16x8*)(lds + PG8_SA(b, h) + aoff + m * 2048 + k * 1024); } while (0)
; #define PG8_MMA(ai, bj, At, Bt) do { __builtin_amdgcn_s_setprio(1); _Pragma("unroll") for (int m = 0; m < 4; ++m) _Pragma("unroll") for (int n = 0; n < 2; ++n) _Pragma("unroll") for (int k = 0; k < 2; ++k) \
;         acc[ai][bj][m][n] = __builtin_amdgcn_mfma_f32_16x16x32_bf16(Bt[n][k], At[m][k], acc[ai][bj][m][n], 0, 0, 0); __builtin_amdgcn_s_setprio(0); } while (0)
; #define PG8_WAIT_V(n) asm volatile("s_waitcnt vmcnt(" #n ")" ::: "memory")
; #define PG8_WAIT_L(n) asm volatile("s_waitcnt lgkmcnt(" #n ")" ::: "memory")
; #define PG8_BAR __builtin_amdgcn_s_barrier()
; #define PG8_SCHED __builtin_amdgcn_sched_barrier(0)
; template <class Epi, class Sched>
; __device__ __forceinline__ void gemm_phase(LAS unsigned char* lds, const Gemm g, const Sched& S, const Epi& E) {
;     ...
;             PG8_WAIT_V(8); PG8_WAIT_L(0); PG8_BAR; PG8_MMA(0, 0, At, B0); PG8_MMA(0, 1, At, B1); PG8_BAR; PG8_SCHED;
;             PG8_LDA(At, 0, 1); PG8_STAGE(PG8_SB(0, 0), b2, voffB); PG8_STAGE(PG8_SB(0, 1), b2 + hstep, voffB); PG8_STAGE(PG8_SA(0, 0), a2, voffA);
;             PG8_WAIT_V(8); PG8_WAIT_L(0); PG8_BAR; PG8_MMA(1, 0, At, B0); PG8_MMA(1, 1, At, B1); PG8_BAR; PG8_SCHED;
	s_setprio 0
	s_waitcnt lgkmcnt(0)
	v_mfma_f32_16x16x32_bf16 v[124:127], v[128:131], v[176:179], v[124:127]
	v_mfma_f32_16x16x32_bf16 v[120:123], v[136:139], v[176:179], v[120:123]
	v_mfma_f32_16x16x32_bf16 v[108:111], v[128:131], v[196:199], v[108:111]
	v_mfma_f32_16x16x32_bf16 v[104:107], v[136:139], v[196:199], v[104:107]
	v_mfma_f32_16x16x32_bf16 v[92:95], v[128:131], v[204:207], v[92:95]
	v_mfma_f32_16x16x32_bf16 v[88:91], v[136:139], v[204:207], v[88:91]
	v_mfma_f32_16x16x32_bf16 v[76:79], v[128:131], v[212:215], v[76:79]
	v_mfma_f32_16x16x32_bf16 v[72:75], v[136:139], v[212:215], v[72:75]
	v_mfma_f32_16x16x32_bf16 v[124:127], v[132:135], v[192:195], v[124:127]
	v_mfma_f32_16x16x32_bf16 v[120:123], v[140:143], v[192:195], v[120:123]
	v_mfma_f32_16x16x32_bf16 v[108:111], v[132:135], v[200:203], v[108:111]
	v_mfma_f32_16x16x32_bf16 v[104:107], v[140:143], v[200:203], v[104:107]
	v_mfma_f32_16x16x32_bf16 v[92:95], v[132:135], v[208:211], v[92:95]
	v_mfma_f32_16x16x32_bf16 v[88:91], v[140:143], v[208:211], v[88:91]
	v_mfma_f32_16x16x32_bf16 v[76:79], v[132:135], v[230:233], v[76:79]
	v_mfma_f32_16x16x32_bf16 v[72:75], v[140:143], v[230:233], v[72:75]
	v_mfma_f32_16x16x32_bf16 v[112:115], v[154:157], v[176:179], v[112:115]
	v_mfma_f32_16x16x32_bf16 v[116:119], v[168:171], v[176:179], v[116:119]
	v_mfma_f32_16x16x32_bf16 v[96:99], v[154:157], v[196:199], v[96:99]
	v_mfma_f32_16x16x32_bf16 v[100:103], v[168:171], v[196:199], v[100:103]
	v_mfma_f32_16x16x32_bf16 v[80:83], v[154:157], v[204:207], v[80:83]
	v_mfma_f32_16x16x32_bf16 v[84:87], v[168:171], v[204:207], v[84:87]
	v_mfma_f32_16x16x32_bf16 v[64:67], v[154:157], v[212:215], v[64:67]
	v_mfma_f32_16x16x32_bf16 v[68:71], v[168:171], v[212:215], v[68:71]
	v_mfma_f32_16x16x32_bf16 v[112:115], v[164:167], v[192:195], v[112:115]
	v_mfma_f32_16x16x32_bf16 v[116:119], v[172:175], v[192:195], v[116:119]
	v_mfma_f32_16x16x32_bf16 v[96:99], v[164:167], v[200:203], v[96:99]
	v_mfma_f32_16x16x32_bf16 v[100:103], v[172:175], v[200:203], v[100:103]
	v_mfma_f32_16x16x32_bf16 v[80:83], v[164:167], v[208:211], v[80:83]
	v_mfma_f32_16x16x32_bf16 v[84:87], v[172:175], v[208:211], v[84:87]
	v_mfma_f32_16x16x32_bf16 v[64:67], v[164:167], v[230:233], v[64:67]
	v_mfma_f32_16x16x32_bf16 v[68:71], v[172:175], v[230:233], v[68:71]
	s_barrier
	s_setprio 1
	s_add_i32 s49, s49, s8
	v_lshl_add_u64 v[158:159], s[24:25], 0, v[184:185]
	s_mov_b32 m0, s49
	ds_read_b128 v[176:179], v163 offset:16384
	ds_read_b128 v[192:195], v163 offset:17408
	ds_read_b128 v[196:199], v163 offset:18432
	ds_read_b128 v[200:203], v163 offset:19456
	ds_read_b128 v[204:207], v163 offset:20480
	ds_read_b128 v[208:211], v163 offset:21504
	ds_read_b128 v[212:215], v163 offset:22528
	ds_read_b128 v[230:233], v163 offset:23552
	global_load_lds_dwordx4 v[158:159], off
	s_add_i32 m0, s49, 0x2000
	s_add_u32 s50, s24, 0x40000
	v_lshl_add_u64 v[216:217], s[24:25], 0, v[144:145]
	s_addc_u32 s51, s25, 0
	s_add_i32 s49, s52, s8
	global_load_lds_dwordx4 v[216:217], off
	v_lshl_add_u64 v[234:235], s[50:51], 0, v[184:185]
	s_mov_b32 m0, s49
	v_lshl_add_u64 v[236:237], s[26:27], 0, v[146:147]
	global_load_lds_dwordx4 v[234:235], off
	v_lshl_add_u64 v[234:235], s[50:51], 0, v[144:145]
	s_add_i32 m0, s49, 0x2000
	s_nop 0
	global_load_lds_dwordx4 v[234:235], off
	v_lshl_add_u64 v[234:235], s[26:27], 0, v[148:149]
	s_mov_b32 m0, s28
	s_nop 0
	global_load_lds_dwordx4 v[234:235], off
	s_mov_b32 m0, s29
	s_nop 0
	global_load_lds_dwordx4 v[236:237], off
	s_waitcnt vmcnt(8)
	s_waitcnt lgkmcnt(0)
	s_barrier
	s_setprio 0
	s_waitcnt lgkmcnt(0)
	v_mfma_f32_16x16x32_bf16 v[60:63], v[128:131], v[176:179], v[60:63]
	v_mfma_f32_16x16x32_bf16 v[56:59], v[136:139], v[176:179], v[56:59]
	v_mfma_f32_16x16x32_bf16 v[44:47], v[128:131], v[196:199], v[44:47]
	v_mfma_f32_16x16x32_bf16 v[40:43], v[136:139], v[196:199], v[40:43]
	v_mfma_f32_16x16x32_bf16 v[28:31], v[128:131], v[204:207], v[28:31]
	v_mfma_f32_16x16x32_bf16 v[24:27], v[136:139], v[204:207], v[24:27]
	v_mfma_f32_16x16x32_bf16 v[12:15], v[128:131], v[212:215], v[12:15]
	v_mfma_f32_16x16x32_bf16 v[8:11], v[136:139], v[212:215], v[8:11]
	v_mfma_f32_16x16x32_bf16 v[60:63], v[132:135], v[192:195], v[60:63]
	v_mfma_f32_16x16x32_bf16 v[56:59], v[140:143], v[192:195], v[56:59]
	v_mfma_f32_16x16x32_bf16 v[44:47], v[132:135], v[200:203], v[44:47]
	v_mfma_f32_16x16x32_bf16 v[40:43], v[140:143], v[200:203], v[40:43]
	v_mfma_f32_16x16x32_bf16 v[28:31], v[132:135], v[208:211], v[28:31]
	v_mfma_f32_16x16x32_bf16 v[24:27], v[140:143], v[208:211], v[24:27]
	v_mfma_f32_16x16x32_bf16 v[12:15], v[132:135], v[230:233], v[12:15]
	v_mfma_f32_16x16x32_bf16 v[8:11], v[140:143], v[230:233], v[8:11]
	v_mfma_f32_16x16x32_bf16 v[48:51], v[154:157], v[176:179], v[48:51]
	v_mfma_f32_16x16x32_bf16 v[52:55], v[168:171], v[176:179], v[52:55]
	v_mfma_f32_16x16x32_bf16 v[32:35], v[154:157], v[196:199], v[32:35]
	v_mfma_f32_16x16x32_bf16 v[36:39], v[168:171], v[196:199], v[36:39]
	v_mfma_f32_16x16x32_bf16 v[16:19], v[154:157], v[204:207], v[16:19]
	v_mfma_f32_16x16x32_bf16 v[20:23], v[168:171], v[204:207], v[20:23]
	v_mfma_f32_16x16x32_bf16 v[0:3], v[154:157], v[212:215], v[0:3]
	v_mfma_f32_16x16x32_bf16 v[4:7], v[168:171], v[212:215], v[4:7]
	v_mfma_f32_16x16x32_bf16 v[48:51], v[164:167], v[192:195], v[48:51]
	v_mfma_f32_16x16x32_bf16 v[52:55], v[172:175], v[192:195], v[52:55]
	v_mfma_f32_16x16x32_bf16 v[32:35], v[164:167], v[200:203], v[32:35]
	v_mfma_f32_16x16x32_bf16 v[36:39], v[172:175], v[200:203], v[36:39]
	v_mfma_f32_16x16x32_bf16 v[16:19], v[164:167], v[208:211], v[16:19]
	v_mfma_f32_16x16x32_bf16 v[20:23], v[172:175], v[208:211], v[20:23]
	v_mfma_f32_16x16x32_bf16 v[0:3], v[164:167], v[230:233], v[0:3]
	v_mfma_f32_16x16x32_bf16 v[4:7], v[172:175], v[230:233], v[4:7]
	s_barrier
; #define PG8_STAGE(bufoff, gbase, voff) do { _Pragma("unroll") for (int _i = 0; _i < 2; ++_i) \
;         __builtin_amdgcn_global_load_lds((const unsigned*)((const char*)(gbase) + (voff)[_i]), (LAS unsigned*)(lds + (bufoff) + ldsw + _i * 8192), 16, 0, 0); } while (0)
; #define PG8_LDA(dst, b, h) do { _Pragma("unroll") for (int m = 0; m < 4; ++m) _Pragma("unroll") for (int k = 0; k < 2; ++k) dst[m][k] = *(const LAS bf16x8*)(lds + PG8_SA(b, h) + aoff + m * 2048 + k * 1024); } while (0)
; #define PG8_LDB(dst, b, h) do { _Pragma("unroll") for (int n = 0; n < 2; ++n) _Pragma("unroll") for (int k = 0; k < 2; ++k) dst[n][k] = *(const LAS bf16x8*)(lds + PG8_SB(b, h) + boff + n * 2048 + k * 1024); } while (0)
; #define PG8_MMA(ai, bj, At, Bt) do { __builtin_amdgcn_s_setprio(1); _Pragma("unroll") for (int m = 0; m < 4; ++m) _Pragma("unroll") for (int n = 0; n < 2; ++n) _Pragma("unroll") for (int k = 0; k < 2; ++k) \
;         acc[ai][bj][m][n] = __builtin_amdgcn_mfma_f32_16x16x32_bf16(Bt[n][k], At[m][k], acc[ai][bj][m][n], 0, 0, 0); __builtin_amdgcn_s_setprio(0); } while (0)
; #define PG8_WAIT_V(n) asm volatile("s_waitcnt vmcnt(" #n ")" ::: "memory")
; #define PG8_WAIT_L(n) asm volatile("s_waitcnt lgkmcnt(" #n ")" ::: "memory")
; #define PG8_BAR __builtin_amdgcn_s_barrier()
; #define PG8_SCHED __builtin_amdgcn_sched_barrier(0)
; template <class Epi, class Sched>
; __device__ __forceinline__ void gemm_phase(LAS unsigned char* lds, const Gemm g, const Sched& S, const Epi& E) {
;     ...
;             PG8_LDB(B0, 1, 0); PG8_LDB(B1, 1, 1); PG8_SCHED; PG8_LDA(At, 1, 0); PG8_STAGE(PG8_SA(0, 1), a2 + hstep, voffA);
;             PG8_WAIT_V(8); PG8_WAIT_L(0); PG8_BAR; PG8_MMA(0, 0, At, B0); PG8_MMA(0, 1, At, B1); PG8_BAR; PG8_SCHED;
	s_setprio 1
	s_add_i32 s49, 0, 0x18000
	s_add_i32 s50, 0, 0x1c000
	v_add_u32_e32 v140, s49, v162
	v_add_u32_e32 v172, s50, v162
	ds_read_b128 v[128:131], v140
	ds_read_b128 v[132:135], v140 offset:1024
	ds_read_b128 v[136:139], v140 offset:2048
	ds_read_b128 v[140:143], v140 offset:3072
	ds_read_b128 v[154:157], v172
	ds_read_b128 v[164:167], v172 offset:1024
	ds_read_b128 v[168:171], v172 offset:2048
	ds_read_b128 v[172:175], v172 offset:3072
	s_add_u32 s26, s26, 0x40000
	s_addc_u32 s27, s27, 0
	s_mov_b32 m0, s30
	v_lshl_add_u64 v[238:239], s[26:27], 0, v[148:149]
	ds_read_b128 v[176:179], v163 offset:32768
	ds_read_b128 v[192:195], v163 offset:33792
	ds_read_b128 v[196:199], v163 offset:34816
	ds_read_b128 v[200:203], v163 offset:35840
	ds_read_b128 v[204:207], v163 offset:36864
	ds_read_b128 v[208:211], v163 offset:37888
	ds_read_b128 v[212:215], v163 offset:38912
	ds_read_b128 v[230:233], v163 offset:39936
	global_load_lds_dwordx4 v[238:239], off
	v_lshl_add_u64 v[238:239], s[26:27], 0, v[146:147]
	s_mov_b32 m0, s31
	s_nop 0
	global_load_lds_dwordx4 v[238:239], off
	s_waitcnt vmcnt(8)
	s_waitcnt lgkmcnt(0)
	s_barrier
	s_setprio 0
	s_waitcnt lgkmcnt(0)
	v_mfma_f32_16x16x32_bf16 v[124:127], v[128:131], v[176:179], v[124:127]
	v_mfma_f32_16x16x32_bf16 v[120:123], v[136:139], v[176:179], v[120:123]
	v_mfma_f32_16x16x32_bf16 v[108:111], v[128:131], v[196:199], v[108:111]
	v_mfma_f32_16x16x32_bf16 v[104:107], v[136:139], v[196:199], v[104:107]
	v_mfma_f32_16x16x32_bf16 v[92:95], v[128:131], v[204:207], v[92:95]
	v_mfma_f32_16x16x32_bf16 v[88:91], v[136:139], v[204:207], v[88:91]
	v_mfma_f32_16x16x32_bf16 v[76:79], v[128:131], v[212:215], v[76:79]
	v_mfma_f32_16x16x32_bf16 v[72:75], v[136:139], v[212:215], v[72:75]
	v_mfma_f32_16x16x32_bf16 v[124:127], v[132:135], v[192:195], v[124:127]
	v_mfma_f32_16x16x32_bf16 v[120:123], v[140:143], v[192:195], v[120:123]
	v_mfma_f32_16x16x32_bf16 v[108:111], v[132:135], v[200:203], v[108:111]
	v_mfma_f32_16x16x32_bf16 v[104:107], v[140:143], v[200:203], v[104:107]
	v_mfma_f32_16x16x32_bf16 v[92:95], v[132:135], v[208:211], v[92:95]
	v_mfma_f32_16x16x32_bf16 v[88:91], v[140:143], v[208:211], v[88:91]
	v_mfma_f32_16x16x32_bf16 v[76:79], v[132:135], v[230:233], v[76:79]
	v_mfma_f32_16x16x32_bf16 v[72:75], v[140:143], v[230:233], v[72:75]
	v_mfma_f32_16x16x32_bf16 v[112:115], v[154:157], v[176:179], v[112:115]
	v_mfma_f32_16x16x32_bf16 v[116:119], v[168:171], v[176:179], v[116:119]
	v_mfma_f32_16x16x32_bf16 v[96:99], v[154:157], v[196:199], v[96:99]
	v_mfma_f32_16x16x32_bf16 v[100:103], v[168:171], v[196:199], v[100:103]
	v_mfma_f32_16x16x32_bf16 v[80:83], v[154:157], v[204:207], v[80:83]
	v_mfma_f32_16x16x32_bf16 v[84:87], v[168:171], v[204:207], v[84:87]
	v_mfma_f32_16x16x32_bf16 v[64:67], v[154:157], v[212:215], v[64:67]
	v_mfma_f32_16x16x32_bf16 v[68:71], v[168:171], v[212:215], v[68:71]
	v_mfma_f32_16x16x32_bf16 v[112:115], v[164:167], v[192:195], v[112:115]
	v_mfma_f32_16x16x32_bf16 v[116:119], v[172:175], v[192:195], v[116:119]
	v_mfma_f32_16x16x32_bf16 v[96:99], v[164:167], v[200:203], v[96:99]
	v_mfma_f32_16x16x32_bf16 v[100:103], v[172:175], v[200:203], v[100:103]
	v_mfma_f32_16x16x32_bf16 v[80:83], v[164:167], v[208:211], v[80:83]
	v_mfma_f32_16x16x32_bf16 v[84:87], v[172:175], v[208:211], v[84:87]
	v_mfma_f32_16x16x32_bf16 v[64:67], v[164:167], v[230:233], v[64:67]
	v_mfma_f32_16x16x32_bf16 v[68:71], v[172:175], v[230:233], v[68:71]
	s_barrier
; #define PG8_STAGE(bufoff, gbase, voff) do { _Pragma("unroll") for (int _i = 0; _i < 2; ++_i) \
;         __builtin_amdgcn_global_load_lds((const unsigned*)((const char*)(gbase) + (voff)[_i]), (LAS unsigned*)(lds + (bufoff) + ldsw + _i * 8192), 16, 0, 0); } while (0)
; #define PG8_LDA(dst, b, h) do { _Pragma("unroll") for (int m = 0; m < 4; ++m) _Pragma("unroll") for (int k = 0; k < 2; ++k) dst[m][k] = *(const LAS bf16x8*)(lds + PG8_SA(b, h) + aoff + m * 2048 + k * 1024); } while (0)
; #define PG8_MMA(ai, bj, At, Bt) do { __builtin_amdgcn_s_setprio(1); _Pragma("unroll") for (int m = 0; m < 4; ++m) _Pragma("unroll") for (int n = 0; n < 2; ++n) _Pragma("unroll") for (int k = 0; k < 2; ++k) \
;         acc[ai][bj][m][n] = __builtin_amdgcn_mfma_f32_16x16x32_bf16(Bt[n][k], At[m][k], acc[ai][bj][m][n], 0, 0, 0); __builtin_amdgcn_s_setprio(0); } while (0)
; #define PG8_WAIT_V(n) asm volatile("s_waitcnt vmcnt(" #n ")" ::: "memory")
; #define PG8_WAIT_L(n) asm volatile("s_waitcnt lgkmcnt(" #n ")" ::: "memory")
; #define PG8_BAR __builtin_amdgcn_s_barrier()
; #define PG8_SCHED __builtin_amdgcn_sched_barrier(0)
; template <class Epi, class Sched>
; __device__ __forceinline__ void gemm_phase(LAS unsigned char* lds, const Gemm g, const Sched& S, const Epi& E) {
;     ...
;             PG8_LDA(At, 1, 1); PG8_STAGE(PG8_SB(1, 0), b3, voffB); PG8_STAGE(PG8_SB(1, 1), b3 + hstep, voffB); PG8_STAGE(PG8_SA(1, 0), a3, voffA);
;             PG8_WAIT_V(8); PG8_WAIT_L(0); PG8_BAR; PG8_MMA(1, 0, At, B0); PG8_MMA(1, 1, At, B1); PG8_BAR; PG8_SCHED;
;         }
;         if (wr == 0) PG8_BAR;
	s_setprio 1
	s_add_i32 s26, s49, s8
	v_lshl_add_u64 v[158:159], v[158:159], 0, s[84:85]
	s_mov_b32 m0, s26
	ds_read_b128 v[176:179], v163 offset:49152
	ds_read_b128 v[192:195], v163 offset:50176
	ds_read_b128 v[196:199], v163 offset:51200
	ds_read_b128 v[200:203], v163 offset:52224
	ds_read_b128 v[204:207], v163 offset:53248
	ds_read_b128 v[208:211], v163 offset:54272
	ds_read_b128 v[212:215], v163 offset:55296
	ds_read_b128 v[230:233], v163 offset:56320
	global_load_lds_dwordx4 v[158:159], off
	s_add_i32 m0, s26, 0x2000
	s_add_u32 s24, s24, 0x40080
	v_lshl_add_u64 v[158:159], v[216:217], 0, s[84:85]
	s_addc_u32 s25, s25, 0
	s_add_i32 s26, s50, s8
	global_load_lds_dwordx4 v[158:159], off
	v_lshl_add_u64 v[158:159], s[24:25], 0, v[184:185]
	s_mov_b32 m0, s26
	s_nop 0
	global_load_lds_dwordx4 v[158:159], off
	v_lshl_add_u64 v[158:159], s[24:25], 0, v[144:145]
	s_add_i32 m0, s26, 0x2000
	s_nop 0
	global_load_lds_dwordx4 v[158:159], off
	v_lshl_add_u64 v[158:159], v[234:235], 0, s[84:85]
	s_mov_b32 m0, s36
	s_nop 0
	global_load_lds_dwordx4 v[158:159], off
	v_lshl_add_u64 v[158:159], v[236:237], 0, s[84:85]
	s_mov_b32 m0, s37
	s_nop 0
	global_load_lds_dwordx4 v[158:159], off
	s_waitcnt vmcnt(8)
	s_waitcnt lgkmcnt(0)
	s_barrier
	s_setprio 0
	s_waitcnt lgkmcnt(0)
	v_mfma_f32_16x16x32_bf16 v[60:63], v[128:131], v[176:179], v[60:63]
	v_mfma_f32_16x16x32_bf16 v[56:59], v[136:139], v[176:179], v[56:59]
	v_mfma_f32_16x16x32_bf16 v[44:47], v[128:131], v[196:199], v[44:47]
	v_mfma_f32_16x16x32_bf16 v[40:43], v[136:139], v[196:199], v[40:43]
	v_mfma_f32_16x16x32_bf16 v[28:31], v[128:131], v[204:207], v[28:31]
	v_mfma_f32_16x16x32_bf16 v[24:27], v[136:139], v[204:207], v[24:27]
	v_mfma_f32_16x16x32_bf16 v[12:15], v[128:131], v[212:215], v[12:15]
	v_mfma_f32_16x16x32_bf16 v[8:11], v[136:139], v[212:215], v[8:11]
	v_mfma_f32_16x16x32_bf16 v[60:63], v[132:135], v[192:195], v[60:63]
	v_mfma_f32_16x16x32_bf16 v[56:59], v[140:143], v[192:195], v[56:59]
	v_mfma_f32_16x16x32_bf16 v[44:47], v[132:135], v[200:203], v[44:47]
	v_mfma_f32_16x16x32_bf16 v[40:43], v[140:143], v[200:203], v[40:43]
	v_mfma_f32_16x16x32_bf16 v[28:31], v[132:135], v[208:211], v[28:31]
	v_mfma_f32_16x16x32_bf16 v[24:27], v[140:143], v[208:211], v[24:27]
	v_mfma_f32_16x16x32_bf16 v[12:15], v[132:135], v[230:233], v[12:15]
	v_mfma_f32_16x16x32_bf16 v[8:11], v[140:143], v[230:233], v[8:11]
	v_mfma_f32_16x16x32_bf16 v[48:51], v[154:157], v[176:179], v[48:51]
	v_mfma_f32_16x16x32_bf16 v[52:55], v[168:171], v[176:179], v[52:55]
	v_mfma_f32_16x16x32_bf16 v[32:35], v[154:157], v[196:199], v[32:35]
	v_mfma_f32_16x16x32_bf16 v[36:39], v[168:171], v[196:199], v[36:39]
	v_mfma_f32_16x16x32_bf16 v[16:19], v[154:157], v[204:207], v[16:19]
	v_mfma_f32_16x16x32_bf16 v[20:23], v[168:171], v[204:207], v[20:23]
	v_mfma_f32_16x16x32_bf16 v[0:3], v[154:157], v[212:215], v[0:3]
	v_mfma_f32_16x16x32_bf16 v[4:7], v[168:171], v[212:215], v[4:7]
	v_mfma_f32_16x16x32_bf16 v[48:51], v[164:167], v[192:195], v[48:51]
	v_mfma_f32_16x16x32_bf16 v[52:55], v[172:175], v[192:195], v[52:55]
	v_mfma_f32_16x16x32_bf16 v[32:35], v[164:167], v[200:203], v[32:35]
	v_mfma_f32_16x16x32_bf16 v[36:39], v[172:175], v[200:203], v[36:39]
	v_mfma_f32_16x16x32_bf16 v[16:19], v[164:167], v[208:211], v[16:19]
	v_mfma_f32_16x16x32_bf16 v[20:23], v[172:175], v[208:211], v[20:23]
	v_mfma_f32_16x16x32_bf16 v[0:3], v[164:167], v[230:233], v[0:3]
	v_mfma_f32_16x16x32_bf16 v[4:7], v[172:175], v[230:233], v[4:7]
	s_barrier
	s_setprio 1
	s_add_i32 s48, s48, 2
	s_add_u32 s22, s22, 0x100
	s_addc_u32 s23, s23, 0
	s_add_u32 s46, s46, 0x100
	s_addc_u32 s47, s47, 0
	s_cmp_gt_u32 s48, 13
	s_cbranch_scc0 .LBB0_744
	s_setprio 0
	s_and_b64 vcc, exec, s[6:7]
	s_cbranch_vccz .LBB0_747
	s_barrier
